# sample-row GEMMs (prepass + split-K sgemm): W pieces first, A fragments in K order, per-K-chunk counted vmcnt waits so compute starts as fragments land
# speedup vs baseline: 1.0005x; 1.0005x over previous
.Linp1_qok:
	s_cmp_gt_u32 s29, 23
	s_cbranch_scc1 .Linp1_next
	s_add_u32 s20, s16, 0x5100000
	s_addc_u32 s21, s17, 0
	s_add_u32 s22, s16, 0x100000
	s_addc_u32 s23, s17, 0
	s_add_u32 s24, s16, 0xd400000
	s_addc_u32 s25, s17, 0
	s_and_b32 s28, s12, 7
	s_lshl_b32 s29, s29, 1
	s_add_u32 s29, s29, s6
	s_lshr_b32 s30, s29, 3
	s_mul_i32 s28, s28, 6
	s_add_u32 s30, s30, s28
	s_and_b32 s31, s29, 7
	s_lshl_b32 s33, s31, 17
	s_lshl_b32 s34, s30, 17
	v_lshlrev_b32_e32 v215, 11, v202
	v_lshl_add_u32 v215, v203, 4, v215
	v_add_u32_e32 v194, s33, v204
	v_add_u32_e32 v198, s34, v215
	v_add_u32_e32 v195, s33, v204
	v_add_u32_e32 v199, s34, v215
	v_add_u32_e32 v196, s33, v204
	v_add_u32_e32 v200, s34, v215
	v_add_u32_e32 v197, s33, v204
	v_add_u32_e32 v201, s34, v215
	v_add_u32_e32 v195, 0x8000, v195
	v_add_u32_e32 v199, 0x8000, v199
	v_add_u32_e32 v196, 0x10000, v196
	v_add_u32_e32 v200, 0x10000, v200
	v_add_u32_e32 v197, 0x18000, v197
	v_add_u32_e32 v201, 0x18000, v201
	s_mul_i32 s33, s31, 0x60000
	s_lshl_b32 s34, s30, 7
	s_add_u32 s33, s33, s34
	v_add_u32_e32 v211, s33, v209
	s_lshr_b32 s35, s30, 3
	s_and_b32 s36, s30, 7
	s_lshl_b32 s36, s36, 8
	s_mov_b32 s37, 0x3f800000
	s_mov_b32 s42, 1
	s_cmp_eq_u32 s35, 0
	s_cselect_b32 s37, 0x3e38aa3b, s37
	s_cselect_b32 s42, 0, s42
	s_cmp_eq_u32 s35, 3
	s_cselect_b32 s37, 0x3e38aa3b, s37
	s_cselect_b32 s42, 0, s42
	s_sub_u32 s43, s35, 1
	s_cmp_gt_u32 s35, 3
	s_cselect_b32 s44, 1, 0
	s_sub_u32 s43, s43, s44
	s_lshl_b32 s43, s43, 20
	s_lshl_b32 s44, s31, 17
	s_add_u32 s43, s43, s44
	s_add_u32 s43, s43, s36
	s_add_u32 s38, s40, s43
	s_addc_u32 s39, s41, 0
	s_add_u32 s38, s38, 0xd280000
	s_addc_u32 s39, s39, 0
	s_lshl_b32 s44, s4, 8
	s_add_u32 s44, s22, s44
	s_addc_u32 s45, s23, 0
	s_lshl_b32 s46, s4, 14
	s_add_i32 m0, s46, 0x0
	s_nop 0
	global_load_lds_dwordx4 v198, s[44:45]
	s_add_i32 m0, s46, 0x400
	s_nop 0
	global_load_lds_dwordx4 v199, s[44:45]
	s_add_i32 m0, s46, 0x800
	s_nop 0
	global_load_lds_dwordx4 v200, s[44:45]
	s_add_i32 m0, s46, 0xc00
	s_nop 0
	global_load_lds_dwordx4 v201, s[44:45]
	s_add_u32 s44, s44, 64
	s_addc_u32 s45, s45, 0
	s_add_i32 m0, s46, 0x1000
	s_nop 0
	global_load_lds_dwordx4 v198, s[44:45]
	s_add_i32 m0, s46, 0x1400
	s_nop 0
	global_load_lds_dwordx4 v199, s[44:45]
	s_add_i32 m0, s46, 0x1800
	s_nop 0
	global_load_lds_dwordx4 v200, s[44:45]
	s_add_i32 m0, s46, 0x1c00
	s_nop 0
	global_load_lds_dwordx4 v201, s[44:45]
	s_add_u32 s44, s44, 64
	s_addc_u32 s45, s45, 0
	s_add_i32 m0, s46, 0x2000
	s_nop 0
	global_load_lds_dwordx4 v198, s[44:45]
	s_add_i32 m0, s46, 0x2400
	s_nop 0
	global_load_lds_dwordx4 v199, s[44:45]
	s_add_i32 m0, s46, 0x2800
	s_nop 0
	global_load_lds_dwordx4 v200, s[44:45]
	s_add_i32 m0, s46, 0x2c00
	s_nop 0
	global_load_lds_dwordx4 v201, s[44:45]
	s_add_u32 s44, s44, 64
	s_addc_u32 s45, s45, 0
	s_add_i32 m0, s46, 0x3000
	s_nop 0
	global_load_lds_dwordx4 v198, s[44:45]
	s_add_i32 m0, s46, 0x3400
	s_nop 0
	global_load_lds_dwordx4 v199, s[44:45]
	s_add_i32 m0, s46, 0x3800
	s_nop 0
	global_load_lds_dwordx4 v200, s[44:45]
	s_add_i32 m0, s46, 0x3c00
	s_nop 0
	global_load_lds_dwordx4 v201, s[44:45]
	global_load_dwordx4 v[66:69], v194, s[20:21] offset:0
	global_load_dwordx4 v[70:73], v195, s[20:21] offset:0
	global_load_dwordx4 v[74:77], v196, s[20:21] offset:0
	global_load_dwordx4 v[78:81], v197, s[20:21] offset:0
	global_load_dwordx4 v[82:85], v194, s[20:21] offset:64
	global_load_dwordx4 v[86:89], v195, s[20:21] offset:64
	global_load_dwordx4 v[90:93], v196, s[20:21] offset:64
	global_load_dwordx4 v[94:97], v197, s[20:21] offset:64
	global_load_dwordx4 v[98:101], v194, s[20:21] offset:128
	global_load_dwordx4 v[102:105], v195, s[20:21] offset:128
	global_load_dwordx4 v[106:109], v196, s[20:21] offset:128
	global_load_dwordx4 v[110:113], v197, s[20:21] offset:128
	global_load_dwordx4 v[114:117], v194, s[20:21] offset:192
	global_load_dwordx4 v[118:121], v195, s[20:21] offset:192
	global_load_dwordx4 v[122:125], v196, s[20:21] offset:192
	global_load_dwordx4 v[126:129], v197, s[20:21] offset:192
	global_load_dwordx4 v[130:133], v194, s[20:21] offset:256
	global_load_dwordx4 v[134:137], v195, s[20:21] offset:256
	global_load_dwordx4 v[138:141], v196, s[20:21] offset:256
	global_load_dwordx4 v[142:145], v197, s[20:21] offset:256
	global_load_dwordx4 v[146:149], v194, s[20:21] offset:320
	global_load_dwordx4 v[150:153], v195, s[20:21] offset:320
	global_load_dwordx4 v[154:157], v196, s[20:21] offset:320
	global_load_dwordx4 v[158:161], v197, s[20:21] offset:320
	global_load_dwordx4 v[162:165], v194, s[20:21] offset:384
	global_load_dwordx4 v[166:169], v195, s[20:21] offset:384
	global_load_dwordx4 v[170:173], v196, s[20:21] offset:384
	global_load_dwordx4 v[174:177], v197, s[20:21] offset:384
	global_load_dwordx4 v[178:181], v194, s[20:21] offset:448
	global_load_dwordx4 v[182:185], v195, s[20:21] offset:448
	global_load_dwordx4 v[186:189], v196, s[20:21] offset:448
	global_load_dwordx4 v[190:193], v197, s[20:21] offset:448
	s_waitcnt vmcnt(28)
	s_barrier
	s_lshl_b32 s47, s5, 15
	v_lshl_add_u32 v214, v205, 4, s47
	ds_read_b128 v[218:221], v214 offset:0
	ds_read_b128 v[222:225], v214 offset:1024
	ds_read_b128 v[226:229], v214 offset:2048
	ds_read_b128 v[230:233], v214 offset:3072
	ds_read_b128 v[234:237], v214 offset:4096
	ds_read_b128 v[238:241], v214 offset:5120
	ds_read_b128 v[242:245], v214 offset:6144
	ds_read_b128 v[246:249], v214 offset:7168
	s_waitcnt lgkmcnt(4)
	v_mfma_f32_16x16x32_bf16 v[2:5], v[218:221], v[66:69], 0
	v_mfma_f32_16x16x32_bf16 v[6:9], v[222:225], v[66:69], 0
	v_mfma_f32_16x16x32_bf16 v[10:13], v[226:229], v[66:69], 0
	v_mfma_f32_16x16x32_bf16 v[14:17], v[230:233], v[66:69], 0
	v_mfma_f32_16x16x32_bf16 v[18:21], v[218:221], v[70:73], 0
	v_mfma_f32_16x16x32_bf16 v[22:25], v[222:225], v[70:73], 0
	v_mfma_f32_16x16x32_bf16 v[26:29], v[226:229], v[70:73], 0
	v_mfma_f32_16x16x32_bf16 v[30:33], v[230:233], v[70:73], 0
	v_mfma_f32_16x16x32_bf16 v[34:37], v[218:221], v[74:77], 0
	v_mfma_f32_16x16x32_bf16 v[38:41], v[222:225], v[74:77], 0
	v_mfma_f32_16x16x32_bf16 v[42:45], v[226:229], v[74:77], 0
	v_mfma_f32_16x16x32_bf16 v[46:49], v[230:233], v[74:77], 0
	v_mfma_f32_16x16x32_bf16 v[50:53], v[218:221], v[78:81], 0
	v_mfma_f32_16x16x32_bf16 v[54:57], v[222:225], v[78:81], 0
	v_mfma_f32_16x16x32_bf16 v[58:61], v[226:229], v[78:81], 0
	v_mfma_f32_16x16x32_bf16 v[62:65], v[230:233], v[78:81], 0
	s_waitcnt vmcnt(24)
	ds_read_b128 v[218:221], v214 offset:8192
	ds_read_b128 v[222:225], v214 offset:9216
	ds_read_b128 v[226:229], v214 offset:10240
	ds_read_b128 v[230:233], v214 offset:11264
	s_waitcnt lgkmcnt(4)
	v_mfma_f32_16x16x32_bf16 v[2:5], v[234:237], v[82:85], v[2:5]
	v_mfma_f32_16x16x32_bf16 v[6:9], v[238:241], v[82:85], v[6:9]
	v_mfma_f32_16x16x32_bf16 v[10:13], v[242:245], v[82:85], v[10:13]
	v_mfma_f32_16x16x32_bf16 v[14:17], v[246:249], v[82:85], v[14:17]
	v_mfma_f32_16x16x32_bf16 v[18:21], v[234:237], v[86:89], v[18:21]
	v_mfma_f32_16x16x32_bf16 v[22:25], v[238:241], v[86:89], v[22:25]
	v_mfma_f32_16x16x32_bf16 v[26:29], v[242:245], v[86:89], v[26:29]
	v_mfma_f32_16x16x32_bf16 v[30:33], v[246:249], v[86:89], v[30:33]
	v_mfma_f32_16x16x32_bf16 v[34:37], v[234:237], v[90:93], v[34:37]
	v_mfma_f32_16x16x32_bf16 v[38:41], v[238:241], v[90:93], v[38:41]
	v_mfma_f32_16x16x32_bf16 v[42:45], v[242:245], v[90:93], v[42:45]
	v_mfma_f32_16x16x32_bf16 v[46:49], v[246:249], v[90:93], v[46:49]
	v_mfma_f32_16x16x32_bf16 v[50:53], v[234:237], v[94:97], v[50:53]
	v_mfma_f32_16x16x32_bf16 v[54:57], v[238:241], v[94:97], v[54:57]
	v_mfma_f32_16x16x32_bf16 v[58:61], v[242:245], v[94:97], v[58:61]
	v_mfma_f32_16x16x32_bf16 v[62:65], v[246:249], v[94:97], v[62:65]
	s_waitcnt vmcnt(20)
	ds_read_b128 v[234:237], v214 offset:12288
	ds_read_b128 v[238:241], v214 offset:13312
	ds_read_b128 v[242:245], v214 offset:14336
	ds_read_b128 v[246:249], v214 offset:15360
	s_waitcnt lgkmcnt(4)
	v_mfma_f32_16x16x32_bf16 v[2:5], v[218:221], v[98:101], v[2:5]
	v_mfma_f32_16x16x32_bf16 v[6:9], v[222:225], v[98:101], v[6:9]
	v_mfma_f32_16x16x32_bf16 v[10:13], v[226:229], v[98:101], v[10:13]
	v_mfma_f32_16x16x32_bf16 v[14:17], v[230:233], v[98:101], v[14:17]
	v_mfma_f32_16x16x32_bf16 v[18:21], v[218:221], v[102:105], v[18:21]
	v_mfma_f32_16x16x32_bf16 v[22:25], v[222:225], v[102:105], v[22:25]
	v_mfma_f32_16x16x32_bf16 v[26:29], v[226:229], v[102:105], v[26:29]
	v_mfma_f32_16x16x32_bf16 v[30:33], v[230:233], v[102:105], v[30:33]
	v_mfma_f32_16x16x32_bf16 v[34:37], v[218:221], v[106:109], v[34:37]
	v_mfma_f32_16x16x32_bf16 v[38:41], v[222:225], v[106:109], v[38:41]
	v_mfma_f32_16x16x32_bf16 v[42:45], v[226:229], v[106:109], v[42:45]
	v_mfma_f32_16x16x32_bf16 v[46:49], v[230:233], v[106:109], v[46:49]
	v_mfma_f32_16x16x32_bf16 v[50:53], v[218:221], v[110:113], v[50:53]
	v_mfma_f32_16x16x32_bf16 v[54:57], v[222:225], v[110:113], v[54:57]
	v_mfma_f32_16x16x32_bf16 v[58:61], v[226:229], v[110:113], v[58:61]
	v_mfma_f32_16x16x32_bf16 v[62:65], v[230:233], v[110:113], v[62:65]
	s_waitcnt vmcnt(16)
	ds_read_b128 v[218:221], v214 offset:16384
	ds_read_b128 v[222:225], v214 offset:17408
	ds_read_b128 v[226:229], v214 offset:18432
	ds_read_b128 v[230:233], v214 offset:19456
	s_waitcnt lgkmcnt(4)
	v_mfma_f32_16x16x32_bf16 v[2:5], v[234:237], v[114:117], v[2:5]
	v_mfma_f32_16x16x32_bf16 v[6:9], v[238:241], v[114:117], v[6:9]
	v_mfma_f32_16x16x32_bf16 v[10:13], v[242:245], v[114:117], v[10:13]
	v_mfma_f32_16x16x32_bf16 v[14:17], v[246:249], v[114:117], v[14:17]
	v_mfma_f32_16x16x32_bf16 v[18:21], v[234:237], v[118:121], v[18:21]
	v_mfma_f32_16x16x32_bf16 v[22:25], v[238:241], v[118:121], v[22:25]
	v_mfma_f32_16x16x32_bf16 v[26:29], v[242:245], v[118:121], v[26:29]
	v_mfma_f32_16x16x32_bf16 v[30:33], v[246:249], v[118:121], v[30:33]
	v_mfma_f32_16x16x32_bf16 v[34:37], v[234:237], v[122:125], v[34:37]
	v_mfma_f32_16x16x32_bf16 v[38:41], v[238:241], v[122:125], v[38:41]
	v_mfma_f32_16x16x32_bf16 v[42:45], v[242:245], v[122:125], v[42:45]
	v_mfma_f32_16x16x32_bf16 v[46:49], v[246:249], v[122:125], v[46:49]
	v_mfma_f32_16x16x32_bf16 v[50:53], v[234:237], v[126:129], v[50:53]
	v_mfma_f32_16x16x32_bf16 v[54:57], v[238:241], v[126:129], v[54:57]
	v_mfma_f32_16x16x32_bf16 v[58:61], v[242:245], v[126:129], v[58:61]
	v_mfma_f32_16x16x32_bf16 v[62:65], v[246:249], v[126:129], v[62:65]
	s_waitcnt vmcnt(12)
	ds_read_b128 v[234:237], v214 offset:20480
	ds_read_b128 v[238:241], v214 offset:21504
	ds_read_b128 v[242:245], v214 offset:22528
	ds_read_b128 v[246:249], v214 offset:23552
	s_waitcnt lgkmcnt(4)
	v_mfma_f32_16x16x32_bf16 v[2:5], v[218:221], v[130:133], v[2:5]
	v_mfma_f32_16x16x32_bf16 v[6:9], v[222:225], v[130:133], v[6:9]
	v_mfma_f32_16x16x32_bf16 v[10:13], v[226:229], v[130:133], v[10:13]
	v_mfma_f32_16x16x32_bf16 v[14:17], v[230:233], v[130:133], v[14:17]
	v_mfma_f32_16x16x32_bf16 v[18:21], v[218:221], v[134:137], v[18:21]
	v_mfma_f32_16x16x32_bf16 v[22:25], v[222:225], v[134:137], v[22:25]
	v_mfma_f32_16x16x32_bf16 v[26:29], v[226:229], v[134:137], v[26:29]
	v_mfma_f32_16x16x32_bf16 v[30:33], v[230:233], v[134:137], v[30:33]
	v_mfma_f32_16x16x32_bf16 v[34:37], v[218:221], v[138:141], v[34:37]
	v_mfma_f32_16x16x32_bf16 v[38:41], v[222:225], v[138:141], v[38:41]
	v_mfma_f32_16x16x32_bf16 v[42:45], v[226:229], v[138:141], v[42:45]
	v_mfma_f32_16x16x32_bf16 v[46:49], v[230:233], v[138:141], v[46:49]
	v_mfma_f32_16x16x32_bf16 v[50:53], v[218:221], v[142:145], v[50:53]
	v_mfma_f32_16x16x32_bf16 v[54:57], v[222:225], v[142:145], v[54:57]
	v_mfma_f32_16x16x32_bf16 v[58:61], v[226:229], v[142:145], v[58:61]
	v_mfma_f32_16x16x32_bf16 v[62:65], v[230:233], v[142:145], v[62:65]
	s_waitcnt vmcnt(8)
	ds_read_b128 v[218:221], v214 offset:24576
	ds_read_b128 v[222:225], v214 offset:25600
	ds_read_b128 v[226:229], v214 offset:26624
	ds_read_b128 v[230:233], v214 offset:27648
	s_waitcnt lgkmcnt(4)
	v_mfma_f32_16x16x32_bf16 v[2:5], v[234:237], v[146:149], v[2:5]
	v_mfma_f32_16x16x32_bf16 v[6:9], v[238:241], v[146:149], v[6:9]
	v_mfma_f32_16x16x32_bf16 v[10:13], v[242:245], v[146:149], v[10:13]
	v_mfma_f32_16x16x32_bf16 v[14:17], v[246:249], v[146:149], v[14:17]
	v_mfma_f32_16x16x32_bf16 v[18:21], v[234:237], v[150:153], v[18:21]
	v_mfma_f32_16x16x32_bf16 v[22:25], v[238:241], v[150:153], v[22:25]
	v_mfma_f32_16x16x32_bf16 v[26:29], v[242:245], v[150:153], v[26:29]
	v_mfma_f32_16x16x32_bf16 v[30:33], v[246:249], v[150:153], v[30:33]
	v_mfma_f32_16x16x32_bf16 v[34:37], v[234:237], v[154:157], v[34:37]
	v_mfma_f32_16x16x32_bf16 v[38:41], v[238:241], v[154:157], v[38:41]
	v_mfma_f32_16x16x32_bf16 v[42:45], v[242:245], v[154:157], v[42:45]
	v_mfma_f32_16x16x32_bf16 v[46:49], v[246:249], v[154:157], v[46:49]
	v_mfma_f32_16x16x32_bf16 v[50:53], v[234:237], v[158:161], v[50:53]
	v_mfma_f32_16x16x32_bf16 v[54:57], v[238:241], v[158:161], v[54:57]
	v_mfma_f32_16x16x32_bf16 v[58:61], v[242:245], v[158:161], v[58:61]
	v_mfma_f32_16x16x32_bf16 v[62:65], v[246:249], v[158:161], v[62:65]
	s_waitcnt vmcnt(4)
	ds_read_b128 v[234:237], v214 offset:28672
	ds_read_b128 v[238:241], v214 offset:29696
	ds_read_b128 v[242:245], v214 offset:30720
	ds_read_b128 v[246:249], v214 offset:31744
	s_waitcnt lgkmcnt(4)
	v_mfma_f32_16x16x32_bf16 v[2:5], v[218:221], v[162:165], v[2:5]
	v_mfma_f32_16x16x32_bf16 v[6:9], v[222:225], v[162:165], v[6:9]
	v_mfma_f32_16x16x32_bf16 v[10:13], v[226:229], v[162:165], v[10:13]
	v_mfma_f32_16x16x32_bf16 v[14:17], v[230:233], v[162:165], v[14:17]
	v_mfma_f32_16x16x32_bf16 v[18:21], v[218:221], v[166:169], v[18:21]
	v_mfma_f32_16x16x32_bf16 v[22:25], v[222:225], v[166:169], v[22:25]
	v_mfma_f32_16x16x32_bf16 v[26:29], v[226:229], v[166:169], v[26:29]
	v_mfma_f32_16x16x32_bf16 v[30:33], v[230:233], v[166:169], v[30:33]
	v_mfma_f32_16x16x32_bf16 v[34:37], v[218:221], v[170:173], v[34:37]
	v_mfma_f32_16x16x32_bf16 v[38:41], v[222:225], v[170:173], v[38:41]
	v_mfma_f32_16x16x32_bf16 v[42:45], v[226:229], v[170:173], v[42:45]
	v_mfma_f32_16x16x32_bf16 v[46:49], v[230:233], v[170:173], v[46:49]
	v_mfma_f32_16x16x32_bf16 v[50:53], v[218:221], v[174:177], v[50:53]
	v_mfma_f32_16x16x32_bf16 v[54:57], v[222:225], v[174:177], v[54:57]
	v_mfma_f32_16x16x32_bf16 v[58:61], v[226:229], v[174:177], v[58:61]
	v_mfma_f32_16x16x32_bf16 v[62:65], v[230:233], v[174:177], v[62:65]
	s_waitcnt vmcnt(0)
	s_waitcnt lgkmcnt(0)
	v_mfma_f32_16x16x32_bf16 v[2:5], v[234:237], v[178:181], v[2:5]
	v_mfma_f32_16x16x32_bf16 v[6:9], v[238:241], v[178:181], v[6:9]
	v_mfma_f32_16x16x32_bf16 v[10:13], v[242:245], v[178:181], v[10:13]
	v_mfma_f32_16x16x32_bf16 v[14:17], v[246:249], v[178:181], v[14:17]
	v_mfma_f32_16x16x32_bf16 v[18:21], v[234:237], v[182:185], v[18:21]
	v_mfma_f32_16x16x32_bf16 v[22:25], v[238:241], v[182:185], v[22:25]
	v_mfma_f32_16x16x32_bf16 v[26:29], v[242:245], v[182:185], v[26:29]
	v_mfma_f32_16x16x32_bf16 v[30:33], v[246:249], v[182:185], v[30:33]
	v_mfma_f32_16x16x32_bf16 v[34:37], v[234:237], v[186:189], v[34:37]
	v_mfma_f32_16x16x32_bf16 v[38:41], v[238:241], v[186:189], v[38:41]
	v_mfma_f32_16x16x32_bf16 v[42:45], v[242:245], v[186:189], v[42:45]
	v_mfma_f32_16x16x32_bf16 v[46:49], v[246:249], v[186:189], v[46:49]
	v_mfma_f32_16x16x32_bf16 v[50:53], v[234:237], v[190:193], v[50:53]
	v_mfma_f32_16x16x32_bf16 v[54:57], v[238:241], v[190:193], v[54:57]
	v_mfma_f32_16x16x32_bf16 v[58:61], v[242:245], v[190:193], v[58:61]
	v_mfma_f32_16x16x32_bf16 v[62:65], v[246:249], v[190:193], v[62:65]
	s_nop 7
	s_barrier
	ds_write_b128 v206, v[2:5] offset:0
	ds_write_b128 v206, v[6:9] offset:1024
	ds_write_b128 v206, v[10:13] offset:2048
	ds_write_b128 v206, v[14:17] offset:3072
	ds_write_b128 v206, v[18:21] offset:4096
	ds_write_b128 v206, v[22:25] offset:5120
	ds_write_b128 v206, v[26:29] offset:6144
	ds_write_b128 v206, v[30:33] offset:7168
	ds_write_b128 v206, v[34:37] offset:8192
	ds_write_b128 v206, v[38:41] offset:9216
	ds_write_b128 v206, v[42:45] offset:10240
	ds_write_b128 v206, v[46:49] offset:11264
	ds_write_b128 v206, v[50:53] offset:12288
	ds_write_b128 v206, v[54:57] offset:13312
	ds_write_b128 v206, v[58:61] offset:14336
	ds_write_b128 v206, v[62:65] offset:15360
	s_waitcnt lgkmcnt(0)
	s_barrier
	ds_read_b128 v[2:5], v207 offset:0
	ds_read_b128 v[6:9], v207 offset:16384
	ds_read_b128 v[10:13], v207 offset:32768
	ds_read_b128 v[14:17], v207 offset:49152
	ds_read_b128 v[18:21], v207 offset:1024
	ds_read_b128 v[22:25], v207 offset:17408
	ds_read_b128 v[26:29], v207 offset:33792
	ds_read_b128 v[30:33], v207 offset:50176
	ds_read_b128 v[34:37], v207 offset:2048
	ds_read_b128 v[38:41], v207 offset:18432
	ds_read_b128 v[42:45], v207 offset:34816
	ds_read_b128 v[46:49], v207 offset:51200
	ds_read_b128 v[50:53], v207 offset:3072
	ds_read_b128 v[54:57], v207 offset:19456
	ds_read_b128 v[58:61], v207 offset:35840
	ds_read_b128 v[62:65], v207 offset:52224
	s_waitcnt lgkmcnt(12)
	v_add_f32_e32 v2, v2, v6
	v_add_f32_e32 v3, v3, v7
	v_add_f32_e32 v4, v4, v8
	v_add_f32_e32 v5, v5, v9
	v_add_f32_e32 v10, v10, v14
	v_add_f32_e32 v11, v11, v15
	v_add_f32_e32 v12, v12, v16
	v_add_f32_e32 v13, v13, v17
	v_add_f32_e32 v2, v2, v10
	v_add_f32_e32 v3, v3, v11
	v_add_f32_e32 v4, v4, v12
	v_add_f32_e32 v5, v5, v13
	s_waitcnt lgkmcnt(8)
	v_add_f32_e32 v18, v18, v22
	v_add_f32_e32 v19, v19, v23
	v_add_f32_e32 v20, v20, v24
	v_add_f32_e32 v21, v21, v25
	v_add_f32_e32 v26, v26, v30
	v_add_f32_e32 v27, v27, v31
	v_add_f32_e32 v28, v28, v32
	v_add_f32_e32 v29, v29, v33
	v_add_f32_e32 v18, v18, v26
	v_add_f32_e32 v19, v19, v27
	v_add_f32_e32 v20, v20, v28
	v_add_f32_e32 v21, v21, v29
	s_waitcnt lgkmcnt(4)
	v_add_f32_e32 v34, v34, v38
	v_add_f32_e32 v35, v35, v39
	v_add_f32_e32 v36, v36, v40
	v_add_f32_e32 v37, v37, v41
	v_add_f32_e32 v42, v42, v46
	v_add_f32_e32 v43, v43, v47
	v_add_f32_e32 v44, v44, v48
	v_add_f32_e32 v45, v45, v49
	v_add_f32_e32 v34, v34, v42
	v_add_f32_e32 v35, v35, v43
	v_add_f32_e32 v36, v36, v44
	v_add_f32_e32 v37, v37, v45
	s_waitcnt lgkmcnt(0)
	v_add_f32_e32 v50, v50, v54
	v_add_f32_e32 v51, v51, v55
	v_add_f32_e32 v52, v52, v56
	v_add_f32_e32 v53, v53, v57
	v_add_f32_e32 v58, v58, v62
	v_add_f32_e32 v59, v59, v63
	v_add_f32_e32 v60, v60, v64
	v_add_f32_e32 v61, v61, v65
	v_add_f32_e32 v50, v50, v58
	v_add_f32_e32 v51, v51, v59
	v_add_f32_e32 v52, v52, v60
	v_add_f32_e32 v53, v53, v61
	s_cmp_eq_u32 s42, 0
	s_cbranch_scc1 .Linp1_nof32
	global_store_dwordx4 v210, v[2:5], s[38:39] offset:0
	global_store_dwordx4 v210, v[18:21], s[38:39] offset:64
	global_store_dwordx4 v210, v[34:37], s[38:39] offset:128
	global_store_dwordx4 v210, v[50:53], s[38:39] offset:192
	s_nop 1

.Lsg3_wg:
	s_and_b32 s26, s25, 7
	s_lshr_b32 s27, s25, 3
	s_lshl_b32 s28, s26, 1
	s_lshr_b32 s29, s27, 4
	s_add_u32 s28, s28, s29
	s_bfe_u32 s29, s27, 0x10003
	s_and_b32 s30, s27, 7
	s_lshl_b32 s31, s24, 3
	s_add_u32 s30, s30, s31
	s_lshl_b32 s31, s29, 10
	s_lshl_b32 s33, s28, 17
	s_add_u32 s33, s33, s31
	s_lshl_b32 s34, s24, 7
	s_add_u32 s33, s33, s34
	s_add_u32 s36, s6, s33
	s_addc_u32 s37, s7, 0
	v_mov_b32_e32 v179, v182
	v_add_u32_e32 v180, 0x10000, v182
	s_lshl_b32 s33, s30, 16
	s_add_u32 s33, s33, s31
	v_add_u32_e32 v178, s33, v182
	s_lshl_b32 s33, s29, 21
	s_lshl_b32 s34, s30, 17
	s_add_u32 s33, s33, s34
	s_lshl_b32 s34, s28, 8
	s_add_u32 s33, s33, s34
	v_add_u32_e32 v181, s33, v183
	s_lshl_b32 s35, s24, 13
	s_cmp_lt_u32 s24, 2
	s_cbranch_scc0 .Lsg3_wonly
	s_add_i32 m0, s35, 0x0
	s_nop 0
	global_load_lds_dwordx4 v179, s[36:37]
	s_add_i32 m0, s35, 0x400
	s_nop 0
	global_load_lds_dwordx4 v180, s[36:37]
	s_add_u32 s36, s36, 32
	s_addc_u32 s37, s37, 0
	s_add_i32 m0, s35, 0x800
	s_nop 0
	global_load_lds_dwordx4 v179, s[36:37]
	s_add_i32 m0, s35, 0xc00
	s_nop 0
	global_load_lds_dwordx4 v180, s[36:37]
	s_add_u32 s36, s36, 32
	s_addc_u32 s37, s37, 0
	s_add_i32 m0, s35, 0x1000
	s_nop 0
	global_load_lds_dwordx4 v179, s[36:37]
	s_add_i32 m0, s35, 0x1400
	s_nop 0
	global_load_lds_dwordx4 v180, s[36:37]
	s_add_u32 s36, s36, 32
	s_addc_u32 s37, s37, 0
	s_add_i32 m0, s35, 0x1800
	s_nop 0
	global_load_lds_dwordx4 v179, s[36:37]
	s_add_i32 m0, s35, 0x1c00
	s_nop 0
	global_load_lds_dwordx4 v180, s[36:37]
	global_load_dwordx4 v[34:37], v178, s[20:21] offset:0
	global_load_dwordx4 v[38:41], v178, s[20:21] offset:32
	global_load_dwordx4 v[42:45], v178, s[20:21] offset:64
	global_load_dwordx4 v[46:49], v178, s[20:21] offset:96
	global_load_dwordx4 v[50:53], v178, s[20:21] offset:128
	global_load_dwordx4 v[54:57], v178, s[20:21] offset:160
	global_load_dwordx4 v[58:61], v178, s[20:21] offset:192
	global_load_dwordx4 v[62:65], v178, s[20:21] offset:224
	global_load_dwordx4 v[66:69], v178, s[20:21] offset:256
	global_load_dwordx4 v[70:73], v178, s[20:21] offset:288
	global_load_dwordx4 v[74:77], v178, s[20:21] offset:320
	global_load_dwordx4 v[78:81], v178, s[20:21] offset:352
	global_load_dwordx4 v[82:85], v178, s[20:21] offset:384
	global_load_dwordx4 v[86:89], v178, s[20:21] offset:416
	global_load_dwordx4 v[90:93], v178, s[20:21] offset:448
	global_load_dwordx4 v[94:97], v178, s[20:21] offset:480
	global_load_dwordx4 v[98:101], v178, s[20:21] offset:512
	global_load_dwordx4 v[102:105], v178, s[20:21] offset:544
	global_load_dwordx4 v[106:109], v178, s[20:21] offset:576
	global_load_dwordx4 v[110:113], v178, s[20:21] offset:608
	global_load_dwordx4 v[114:117], v178, s[20:21] offset:640
	global_load_dwordx4 v[118:121], v178, s[20:21] offset:672
	global_load_dwordx4 v[122:125], v178, s[20:21] offset:704
	global_load_dwordx4 v[126:129], v178, s[20:21] offset:736
	global_load_dwordx4 v[130:133], v178, s[20:21] offset:768
	global_load_dwordx4 v[134:137], v178, s[20:21] offset:800
	global_load_dwordx4 v[138:141], v178, s[20:21] offset:832
	global_load_dwordx4 v[142:145], v178, s[20:21] offset:864
	global_load_dwordx4 v[146:149], v178, s[20:21] offset:896
	global_load_dwordx4 v[150:153], v178, s[20:21] offset:928
	global_load_dwordx4 v[154:157], v178, s[20:21] offset:960
	global_load_dwordx4 v[158:161], v178, s[20:21] offset:992
	s_waitcnt vmcnt(31)
	s_barrier
	s_branch .Lsg3_cmp
	s_branch .Lsg3_issued

.Lsg3_cmp:
	ds_read_b128 v[162:165], v184 offset:0
	ds_read_b128 v[166:169], v184 offset:1024
	ds_read_b128 v[170:173], v184 offset:2048
	ds_read_b128 v[174:177], v184 offset:3072
	s_waitcnt lgkmcnt(2)
	v_mfma_f32_32x32x16_bf16 v[2:17], v[34:37], v[162:165], 0
	v_mfma_f32_32x32x16_bf16 v[18:33], v[34:37], v[166:169], 0
	ds_read_b128 v[162:165], v184 offset:4096
	ds_read_b128 v[166:169], v184 offset:5120
	s_waitcnt lgkmcnt(2)
	s_waitcnt vmcnt(30)
	v_mfma_f32_32x32x16_bf16 v[2:17], v[38:41], v[170:173], v[2:17]
	v_mfma_f32_32x32x16_bf16 v[18:33], v[38:41], v[174:177], v[18:33]
	ds_read_b128 v[170:173], v184 offset:6144
	ds_read_b128 v[174:177], v184 offset:7168
	s_waitcnt lgkmcnt(2)
	s_waitcnt vmcnt(29)
	v_mfma_f32_32x32x16_bf16 v[2:17], v[42:45], v[162:165], v[2:17]
	v_mfma_f32_32x32x16_bf16 v[18:33], v[42:45], v[166:169], v[18:33]
	ds_read_b128 v[162:165], v184 offset:8192
	ds_read_b128 v[166:169], v184 offset:9216
	s_waitcnt lgkmcnt(2)
	s_waitcnt vmcnt(28)
	v_mfma_f32_32x32x16_bf16 v[2:17], v[46:49], v[170:173], v[2:17]
	v_mfma_f32_32x32x16_bf16 v[18:33], v[46:49], v[174:177], v[18:33]
	ds_read_b128 v[170:173], v184 offset:10240
	ds_read_b128 v[174:177], v184 offset:11264
	s_waitcnt lgkmcnt(2)
	s_waitcnt vmcnt(27)
	v_mfma_f32_32x32x16_bf16 v[2:17], v[50:53], v[162:165], v[2:17]
	v_mfma_f32_32x32x16_bf16 v[18:33], v[50:53], v[166:169], v[18:33]
	ds_read_b128 v[162:165], v184 offset:12288
	ds_read_b128 v[166:169], v184 offset:13312
	s_waitcnt lgkmcnt(2)
	s_waitcnt vmcnt(26)
	v_mfma_f32_32x32x16_bf16 v[2:17], v[54:57], v[170:173], v[2:17]
	v_mfma_f32_32x32x16_bf16 v[18:33], v[54:57], v[174:177], v[18:33]
	ds_read_b128 v[170:173], v184 offset:14336
	ds_read_b128 v[174:177], v184 offset:15360
	s_waitcnt lgkmcnt(2)
	s_waitcnt vmcnt(25)
	v_mfma_f32_32x32x16_bf16 v[2:17], v[58:61], v[162:165], v[2:17]
	v_mfma_f32_32x32x16_bf16 v[18:33], v[58:61], v[166:169], v[18:33]
	ds_read_b128 v[162:165], v184 offset:16384
	ds_read_b128 v[166:169], v184 offset:17408
	s_waitcnt lgkmcnt(2)
	s_waitcnt vmcnt(24)
	v_mfma_f32_32x32x16_bf16 v[2:17], v[62:65], v[170:173], v[2:17]
	v_mfma_f32_32x32x16_bf16 v[18:33], v[62:65], v[174:177], v[18:33]
	ds_read_b128 v[170:173], v184 offset:18432
	ds_read_b128 v[174:177], v184 offset:19456
	s_waitcnt lgkmcnt(2)
	s_waitcnt vmcnt(23)
	v_mfma_f32_32x32x16_bf16 v[2:17], v[66:69], v[162:165], v[2:17]
	v_mfma_f32_32x32x16_bf16 v[18:33], v[66:69], v[166:169], v[18:33]
	ds_read_b128 v[162:165], v184 offset:20480
	ds_read_b128 v[166:169], v184 offset:21504
	s_waitcnt lgkmcnt(2)
	s_waitcnt vmcnt(22)
	v_mfma_f32_32x32x16_bf16 v[2:17], v[70:73], v[170:173], v[2:17]
	v_mfma_f32_32x32x16_bf16 v[18:33], v[70:73], v[174:177], v[18:33]
	ds_read_b128 v[170:173], v184 offset:22528
	ds_read_b128 v[174:177], v184 offset:23552
	s_waitcnt lgkmcnt(2)
	s_waitcnt vmcnt(21)
	v_mfma_f32_32x32x16_bf16 v[2:17], v[74:77], v[162:165], v[2:17]
	v_mfma_f32_32x32x16_bf16 v[18:33], v[74:77], v[166:169], v[18:33]
	ds_read_b128 v[162:165], v184 offset:24576
	ds_read_b128 v[166:169], v184 offset:25600
	s_waitcnt lgkmcnt(2)
	s_waitcnt vmcnt(20)
	v_mfma_f32_32x32x16_bf16 v[2:17], v[78:81], v[170:173], v[2:17]
	v_mfma_f32_32x32x16_bf16 v[18:33], v[78:81], v[174:177], v[18:33]
	ds_read_b128 v[170:173], v184 offset:26624
	ds_read_b128 v[174:177], v184 offset:27648
	s_waitcnt lgkmcnt(2)
	s_waitcnt vmcnt(19)
	v_mfma_f32_32x32x16_bf16 v[2:17], v[82:85], v[162:165], v[2:17]
	v_mfma_f32_32x32x16_bf16 v[18:33], v[82:85], v[166:169], v[18:33]
	ds_read_b128 v[162:165], v184 offset:28672
	ds_read_b128 v[166:169], v184 offset:29696
	s_waitcnt lgkmcnt(2)
	s_waitcnt vmcnt(18)
	v_mfma_f32_32x32x16_bf16 v[2:17], v[86:89], v[170:173], v[2:17]
	v_mfma_f32_32x32x16_bf16 v[18:33], v[86:89], v[174:177], v[18:33]
	ds_read_b128 v[170:173], v184 offset:30720
	ds_read_b128 v[174:177], v184 offset:31744
	s_waitcnt lgkmcnt(2)
	s_waitcnt vmcnt(17)
	v_mfma_f32_32x32x16_bf16 v[2:17], v[90:93], v[162:165], v[2:17]
	v_mfma_f32_32x32x16_bf16 v[18:33], v[90:93], v[166:169], v[18:33]
	ds_read_b128 v[162:165], v184 offset:32768
	ds_read_b128 v[166:169], v184 offset:33792
	s_waitcnt lgkmcnt(2)
	s_waitcnt vmcnt(16)
	v_mfma_f32_32x32x16_bf16 v[2:17], v[94:97], v[170:173], v[2:17]
	v_mfma_f32_32x32x16_bf16 v[18:33], v[94:97], v[174:177], v[18:33]
	ds_read_b128 v[170:173], v184 offset:34816
	ds_read_b128 v[174:177], v184 offset:35840
	s_waitcnt lgkmcnt(2)
	s_waitcnt vmcnt(15)
	v_mfma_f32_32x32x16_bf16 v[2:17], v[98:101], v[162:165], v[2:17]
	v_mfma_f32_32x32x16_bf16 v[18:33], v[98:101], v[166:169], v[18:33]
	ds_read_b128 v[162:165], v184 offset:36864
	ds_read_b128 v[166:169], v184 offset:37888
	s_waitcnt lgkmcnt(2)
	s_waitcnt vmcnt(14)
	v_mfma_f32_32x32x16_bf16 v[2:17], v[102:105], v[170:173], v[2:17]
	v_mfma_f32_32x32x16_bf16 v[18:33], v[102:105], v[174:177], v[18:33]
	ds_read_b128 v[170:173], v184 offset:38912
	ds_read_b128 v[174:177], v184 offset:39936
	s_waitcnt lgkmcnt(2)
	s_waitcnt vmcnt(13)
	v_mfma_f32_32x32x16_bf16 v[2:17], v[106:109], v[162:165], v[2:17]
	v_mfma_f32_32x32x16_bf16 v[18:33], v[106:109], v[166:169], v[18:33]
	ds_read_b128 v[162:165], v184 offset:40960
	ds_read_b128 v[166:169], v184 offset:41984
	s_waitcnt lgkmcnt(2)
	s_waitcnt vmcnt(12)
	v_mfma_f32_32x32x16_bf16 v[2:17], v[110:113], v[170:173], v[2:17]
	v_mfma_f32_32x32x16_bf16 v[18:33], v[110:113], v[174:177], v[18:33]
	ds_read_b128 v[170:173], v184 offset:43008
	ds_read_b128 v[174:177], v184 offset:44032
	s_waitcnt lgkmcnt(2)
	s_waitcnt vmcnt(11)
	v_mfma_f32_32x32x16_bf16 v[2:17], v[114:117], v[162:165], v[2:17]
	v_mfma_f32_32x32x16_bf16 v[18:33], v[114:117], v[166:169], v[18:33]
	ds_read_b128 v[162:165], v184 offset:45056
	ds_read_b128 v[166:169], v184 offset:46080
	s_waitcnt lgkmcnt(2)
	s_waitcnt vmcnt(10)
	v_mfma_f32_32x32x16_bf16 v[2:17], v[118:121], v[170:173], v[2:17]
	v_mfma_f32_32x32x16_bf16 v[18:33], v[118:121], v[174:177], v[18:33]
	ds_read_b128 v[170:173], v184 offset:47104
	ds_read_b128 v[174:177], v184 offset:48128
	s_waitcnt lgkmcnt(2)
	s_waitcnt vmcnt(9)
	v_mfma_f32_32x32x16_bf16 v[2:17], v[122:125], v[162:165], v[2:17]
	v_mfma_f32_32x32x16_bf16 v[18:33], v[122:125], v[166:169], v[18:33]
	ds_read_b128 v[162:165], v184 offset:49152
	ds_read_b128 v[166:169], v184 offset:50176
	s_waitcnt lgkmcnt(2)
	s_waitcnt vmcnt(8)
	v_mfma_f32_32x32x16_bf16 v[2:17], v[126:129], v[170:173], v[2:17]
	v_mfma_f32_32x32x16_bf16 v[18:33], v[126:129], v[174:177], v[18:33]
	ds_read_b128 v[170:173], v184 offset:51200
	ds_read_b128 v[174:177], v184 offset:52224
	s_waitcnt lgkmcnt(2)
	s_waitcnt vmcnt(7)
	v_mfma_f32_32x32x16_bf16 v[2:17], v[130:133], v[162:165], v[2:17]
	v_mfma_f32_32x32x16_bf16 v[18:33], v[130:133], v[166:169], v[18:33]
	ds_read_b128 v[162:165], v184 offset:53248
	ds_read_b128 v[166:169], v184 offset:54272
	s_waitcnt lgkmcnt(2)
	s_waitcnt vmcnt(6)
	v_mfma_f32_32x32x16_bf16 v[2:17], v[134:137], v[170:173], v[2:17]
	v_mfma_f32_32x32x16_bf16 v[18:33], v[134:137], v[174:177], v[18:33]
	ds_read_b128 v[170:173], v184 offset:55296
	ds_read_b128 v[174:177], v184 offset:56320
	s_waitcnt lgkmcnt(2)
	s_waitcnt vmcnt(5)
	v_mfma_f32_32x32x16_bf16 v[2:17], v[138:141], v[162:165], v[2:17]
	v_mfma_f32_32x32x16_bf16 v[18:33], v[138:141], v[166:169], v[18:33]
	ds_read_b128 v[162:165], v184 offset:57344
	ds_read_b128 v[166:169], v184 offset:58368
	s_waitcnt lgkmcnt(2)
	s_waitcnt vmcnt(4)
	v_mfma_f32_32x32x16_bf16 v[2:17], v[142:145], v[170:173], v[2:17]
	v_mfma_f32_32x32x16_bf16 v[18:33], v[142:145], v[174:177], v[18:33]
	ds_read_b128 v[170:173], v184 offset:59392
	ds_read_b128 v[174:177], v184 offset:60416
	s_waitcnt lgkmcnt(2)
	s_waitcnt vmcnt(3)
	v_mfma_f32_32x32x16_bf16 v[2:17], v[146:149], v[162:165], v[2:17]
	v_mfma_f32_32x32x16_bf16 v[18:33], v[146:149], v[166:169], v[18:33]
	ds_read_b128 v[162:165], v184 offset:61440
	ds_read_b128 v[166:169], v184 offset:62464
	s_waitcnt lgkmcnt(2)
	s_waitcnt vmcnt(2)
	v_mfma_f32_32x32x16_bf16 v[2:17], v[150:153], v[170:173], v[2:17]
	v_mfma_f32_32x32x16_bf16 v[18:33], v[150:153], v[174:177], v[18:33]
	ds_read_b128 v[170:173], v184 offset:63488
	ds_read_b128 v[174:177], v184 offset:64512
	s_waitcnt lgkmcnt(2)
	s_waitcnt vmcnt(1)
	v_mfma_f32_32x32x16_bf16 v[2:17], v[154:157], v[162:165], v[2:17]
	v_mfma_f32_32x32x16_bf16 v[18:33], v[154:157], v[166:169], v[18:33]
	s_waitcnt lgkmcnt(0)
	s_waitcnt vmcnt(0)
	v_mfma_f32_32x32x16_bf16 v[2:17], v[158:161], v[170:173], v[2:17]
	v_mfma_f32_32x32x16_bf16 v[18:33], v[158:161], v[174:177], v[18:33]
	s_nop 15
	s_nop 3
	global_store_dword v181, v2, s[22:23]
	global_store_dword v181, v18, s[22:23] offset:128
	v_add_u32_e32 v188, 0x1000, v181
	global_store_dword v188, v3, s[22:23]
	global_store_dword v188, v19, s[22:23] offset:128
	v_add_u32_e32 v187, 0x2000, v181
	global_store_dword v187, v4, s[22:23]
	global_store_dword v187, v20, s[22:23] offset:128
	v_add_u32_e32 v188, 0x3000, v181
	global_store_dword v188, v5, s[22:23]
	global_store_dword v188, v21, s[22:23] offset:128
	v_add_u32_e32 v187, 0x8000, v181
	global_store_dword v187, v6, s[22:23]
	global_store_dword v187, v22, s[22:23] offset:128
	v_add_u32_e32 v188, 0x9000, v181
	global_store_dword v188, v7, s[22:23]
	global_store_dword v188, v23, s[22:23] offset:128
	v_add_u32_e32 v187, 0xa000, v181
	global_store_dword v187, v8, s[22:23]
	global_store_dword v187, v24, s[22:23] offset:128
	v_add_u32_e32 v188, 0xb000, v181
	global_store_dword v188, v9, s[22:23]
	global_store_dword v188, v25, s[22:23] offset:128
	v_add_u32_e32 v187, 0x10000, v181
	global_store_dword v187, v10, s[22:23]
	global_store_dword v187, v26, s[22:23] offset:128
	v_add_u32_e32 v188, 0x11000, v181
	global_store_dword v188, v11, s[22:23]
	global_store_dword v188, v27, s[22:23] offset:128
	v_add_u32_e32 v187, 0x12000, v181
	global_store_dword v187, v12, s[22:23]
	global_store_dword v187, v28, s[22:23] offset:128
	v_add_u32_e32 v188, 0x13000, v181
	global_store_dword v188, v13, s[22:23]
	global_store_dword v188, v29, s[22:23] offset:128
	v_add_u32_e32 v187, 0x18000, v181
	global_store_dword v187, v14, s[22:23]
	global_store_dword v187, v30, s[22:23] offset:128
	v_add_u32_e32 v188, 0x19000, v181
	global_store_dword v188, v15, s[22:23]
	global_store_dword v188, v31, s[22:23] offset:128
	v_add_u32_e32 v187, 0x1a000, v181
	global_store_dword v187, v16, s[22:23]
	global_store_dword v187, v32, s[22:23] offset:128
	v_add_u32_e32 v188, 0x1b000, v181
	global_store_dword v188, v17, s[22:23]
	global_store_dword v188, v33, s[22:23] offset:128

.Lsmp5_unit:
	s_add_u32 s20, s16, 0x5100000
	s_addc_u32 s21, s17, 0
	s_add_u32 s22, s16, 0x900000
	s_addc_u32 s23, s17, 0
	s_add_u32 s24, s16, 0xf400000
	s_addc_u32 s25, s17, 0
	s_and_b32 s28, s12, 7
	s_lshr_b32 s29, s12, 3
	s_lshl_b32 s29, s29, 1
	s_add_u32 s29, s29, s6
	s_lshr_b32 s30, s29, 3
	s_lshl_b32 s28, s28, 3
	s_add_u32 s30, s30, s28
	s_and_b32 s31, s29, 7
	s_lshl_b32 s33, s31, 17
	s_lshl_b32 s34, s30, 17
	v_lshlrev_b32_e32 v215, 11, v202
	v_lshl_add_u32 v215, v203, 4, v215
	v_add_u32_e32 v194, s33, v204
	v_add_u32_e32 v198, s34, v215
	v_add_u32_e32 v195, s33, v204
	v_add_u32_e32 v199, s34, v215
	v_add_u32_e32 v196, s33, v204
	v_add_u32_e32 v200, s34, v215
	v_add_u32_e32 v197, s33, v204
	v_add_u32_e32 v201, s34, v215
	v_add_u32_e32 v195, 0x8000, v195
	v_add_u32_e32 v199, 0x8000, v199
	v_add_u32_e32 v196, 0x10000, v196
	v_add_u32_e32 v200, 0x10000, v200
	v_add_u32_e32 v197, 0x18000, v197
	v_add_u32_e32 v201, 0x18000, v201
	s_lshl_b32 s33, s31, 19
	s_lshl_b32 s34, s30, 7
	s_add_u32 s33, s33, s34
	v_add_u32_e32 v209, s33, v208
	s_lshl_b32 s44, s4, 8
	s_add_u32 s44, s22, s44
	s_addc_u32 s45, s23, 0
	s_lshl_b32 s46, s4, 14
	s_add_i32 m0, s46, 0x0
	s_nop 0
	global_load_lds_dwordx4 v198, s[44:45]
	s_add_i32 m0, s46, 0x400
	s_nop 0
	global_load_lds_dwordx4 v199, s[44:45]
	s_add_i32 m0, s46, 0x800
	s_nop 0
	global_load_lds_dwordx4 v200, s[44:45]
	s_add_i32 m0, s46, 0xc00
	s_nop 0
	global_load_lds_dwordx4 v201, s[44:45]
	s_add_u32 s44, s44, 64
	s_addc_u32 s45, s45, 0
	s_add_i32 m0, s46, 0x1000
	s_nop 0
	global_load_lds_dwordx4 v198, s[44:45]
	s_add_i32 m0, s46, 0x1400
	s_nop 0
	global_load_lds_dwordx4 v199, s[44:45]
	s_add_i32 m0, s46, 0x1800
	s_nop 0
	global_load_lds_dwordx4 v200, s[44:45]
	s_add_i32 m0, s46, 0x1c00
	s_nop 0
	global_load_lds_dwordx4 v201, s[44:45]
	s_add_u32 s44, s44, 64
	s_addc_u32 s45, s45, 0
	s_add_i32 m0, s46, 0x2000
	s_nop 0
	global_load_lds_dwordx4 v198, s[44:45]
	s_add_i32 m0, s46, 0x2400
	s_nop 0
	global_load_lds_dwordx4 v199, s[44:45]
	s_add_i32 m0, s46, 0x2800
	s_nop 0
	global_load_lds_dwordx4 v200, s[44:45]
	s_add_i32 m0, s46, 0x2c00
	s_nop 0
	global_load_lds_dwordx4 v201, s[44:45]
	s_add_u32 s44, s44, 64
	s_addc_u32 s45, s45, 0
	s_add_i32 m0, s46, 0x3000
	s_nop 0
	global_load_lds_dwordx4 v198, s[44:45]
	s_add_i32 m0, s46, 0x3400
	s_nop 0
	global_load_lds_dwordx4 v199, s[44:45]
	s_add_i32 m0, s46, 0x3800
	s_nop 0
	global_load_lds_dwordx4 v200, s[44:45]
	s_add_i32 m0, s46, 0x3c00
	s_nop 0
	global_load_lds_dwordx4 v201, s[44:45]
	global_load_dwordx4 v[66:69], v194, s[20:21] offset:0
	global_load_dwordx4 v[70:73], v195, s[20:21] offset:0
	global_load_dwordx4 v[74:77], v196, s[20:21] offset:0
	global_load_dwordx4 v[78:81], v197, s[20:21] offset:0
	global_load_dwordx4 v[82:85], v194, s[20:21] offset:64
	global_load_dwordx4 v[86:89], v195, s[20:21] offset:64
	global_load_dwordx4 v[90:93], v196, s[20:21] offset:64
	global_load_dwordx4 v[94:97], v197, s[20:21] offset:64
	global_load_dwordx4 v[98:101], v194, s[20:21] offset:128
	global_load_dwordx4 v[102:105], v195, s[20:21] offset:128
	global_load_dwordx4 v[106:109], v196, s[20:21] offset:128
	global_load_dwordx4 v[110:113], v197, s[20:21] offset:128
	global_load_dwordx4 v[114:117], v194, s[20:21] offset:192
	global_load_dwordx4 v[118:121], v195, s[20:21] offset:192
	global_load_dwordx4 v[122:125], v196, s[20:21] offset:192
	global_load_dwordx4 v[126:129], v197, s[20:21] offset:192
	global_load_dwordx4 v[130:133], v194, s[20:21] offset:256
	global_load_dwordx4 v[134:137], v195, s[20:21] offset:256
	global_load_dwordx4 v[138:141], v196, s[20:21] offset:256
	global_load_dwordx4 v[142:145], v197, s[20:21] offset:256
	global_load_dwordx4 v[146:149], v194, s[20:21] offset:320
	global_load_dwordx4 v[150:153], v195, s[20:21] offset:320
	global_load_dwordx4 v[154:157], v196, s[20:21] offset:320
	global_load_dwordx4 v[158:161], v197, s[20:21] offset:320
	global_load_dwordx4 v[162:165], v194, s[20:21] offset:384
	global_load_dwordx4 v[166:169], v195, s[20:21] offset:384
	global_load_dwordx4 v[170:173], v196, s[20:21] offset:384
	global_load_dwordx4 v[174:177], v197, s[20:21] offset:384
	global_load_dwordx4 v[178:181], v194, s[20:21] offset:448
	global_load_dwordx4 v[182:185], v195, s[20:21] offset:448
	global_load_dwordx4 v[186:189], v196, s[20:21] offset:448
	global_load_dwordx4 v[190:193], v197, s[20:21] offset:448
	s_waitcnt vmcnt(28)
	s_barrier
	s_lshl_b32 s47, s5, 15
	v_lshl_add_u32 v214, v205, 4, s47
	ds_read_b128 v[218:221], v214 offset:0
	ds_read_b128 v[222:225], v214 offset:1024
	ds_read_b128 v[226:229], v214 offset:2048
	ds_read_b128 v[230:233], v214 offset:3072
	ds_read_b128 v[234:237], v214 offset:4096
	ds_read_b128 v[238:241], v214 offset:5120
	ds_read_b128 v[242:245], v214 offset:6144
	ds_read_b128 v[246:249], v214 offset:7168
	s_waitcnt lgkmcnt(4)
	v_mfma_f32_16x16x32_bf16 v[2:5], v[218:221], v[66:69], 0
	v_mfma_f32_16x16x32_bf16 v[6:9], v[222:225], v[66:69], 0
	v_mfma_f32_16x16x32_bf16 v[10:13], v[226:229], v[66:69], 0
	v_mfma_f32_16x16x32_bf16 v[14:17], v[230:233], v[66:69], 0
	v_mfma_f32_16x16x32_bf16 v[18:21], v[218:221], v[70:73], 0
	v_mfma_f32_16x16x32_bf16 v[22:25], v[222:225], v[70:73], 0
	v_mfma_f32_16x16x32_bf16 v[26:29], v[226:229], v[70:73], 0
	v_mfma_f32_16x16x32_bf16 v[30:33], v[230:233], v[70:73], 0
	v_mfma_f32_16x16x32_bf16 v[34:37], v[218:221], v[74:77], 0
	v_mfma_f32_16x16x32_bf16 v[38:41], v[222:225], v[74:77], 0
	v_mfma_f32_16x16x32_bf16 v[42:45], v[226:229], v[74:77], 0
	v_mfma_f32_16x16x32_bf16 v[46:49], v[230:233], v[74:77], 0
	v_mfma_f32_16x16x32_bf16 v[50:53], v[218:221], v[78:81], 0
	v_mfma_f32_16x16x32_bf16 v[54:57], v[222:225], v[78:81], 0
	v_mfma_f32_16x16x32_bf16 v[58:61], v[226:229], v[78:81], 0
	v_mfma_f32_16x16x32_bf16 v[62:65], v[230:233], v[78:81], 0
	s_waitcnt vmcnt(24)
	ds_read_b128 v[218:221], v214 offset:8192
	ds_read_b128 v[222:225], v214 offset:9216
	ds_read_b128 v[226:229], v214 offset:10240
	ds_read_b128 v[230:233], v214 offset:11264
	s_waitcnt lgkmcnt(4)
	v_mfma_f32_16x16x32_bf16 v[2:5], v[234:237], v[82:85], v[2:5]
	v_mfma_f32_16x16x32_bf16 v[6:9], v[238:241], v[82:85], v[6:9]
	v_mfma_f32_16x16x32_bf16 v[10:13], v[242:245], v[82:85], v[10:13]
	v_mfma_f32_16x16x32_bf16 v[14:17], v[246:249], v[82:85], v[14:17]
	v_mfma_f32_16x16x32_bf16 v[18:21], v[234:237], v[86:89], v[18:21]
	v_mfma_f32_16x16x32_bf16 v[22:25], v[238:241], v[86:89], v[22:25]
	v_mfma_f32_16x16x32_bf16 v[26:29], v[242:245], v[86:89], v[26:29]
	v_mfma_f32_16x16x32_bf16 v[30:33], v[246:249], v[86:89], v[30:33]
	v_mfma_f32_16x16x32_bf16 v[34:37], v[234:237], v[90:93], v[34:37]
	v_mfma_f32_16x16x32_bf16 v[38:41], v[238:241], v[90:93], v[38:41]
	v_mfma_f32_16x16x32_bf16 v[42:45], v[242:245], v[90:93], v[42:45]
	v_mfma_f32_16x16x32_bf16 v[46:49], v[246:249], v[90:93], v[46:49]
	v_mfma_f32_16x16x32_bf16 v[50:53], v[234:237], v[94:97], v[50:53]
	v_mfma_f32_16x16x32_bf16 v[54:57], v[238:241], v[94:97], v[54:57]
	v_mfma_f32_16x16x32_bf16 v[58:61], v[242:245], v[94:97], v[58:61]
	v_mfma_f32_16x16x32_bf16 v[62:65], v[246:249], v[94:97], v[62:65]
	s_waitcnt vmcnt(20)
	ds_read_b128 v[234:237], v214 offset:12288
	ds_read_b128 v[238:241], v214 offset:13312
	ds_read_b128 v[242:245], v214 offset:14336
	ds_read_b128 v[246:249], v214 offset:15360
	s_waitcnt lgkmcnt(4)
	v_mfma_f32_16x16x32_bf16 v[2:5], v[218:221], v[98:101], v[2:5]
	v_mfma_f32_16x16x32_bf16 v[6:9], v[222:225], v[98:101], v[6:9]
	v_mfma_f32_16x16x32_bf16 v[10:13], v[226:229], v[98:101], v[10:13]
	v_mfma_f32_16x16x32_bf16 v[14:17], v[230:233], v[98:101], v[14:17]
	v_mfma_f32_16x16x32_bf16 v[18:21], v[218:221], v[102:105], v[18:21]
	v_mfma_f32_16x16x32_bf16 v[22:25], v[222:225], v[102:105], v[22:25]
	v_mfma_f32_16x16x32_bf16 v[26:29], v[226:229], v[102:105], v[26:29]
	v_mfma_f32_16x16x32_bf16 v[30:33], v[230:233], v[102:105], v[30:33]
	v_mfma_f32_16x16x32_bf16 v[34:37], v[218:221], v[106:109], v[34:37]
	v_mfma_f32_16x16x32_bf16 v[38:41], v[222:225], v[106:109], v[38:41]
	v_mfma_f32_16x16x32_bf16 v[42:45], v[226:229], v[106:109], v[42:45]
	v_mfma_f32_16x16x32_bf16 v[46:49], v[230:233], v[106:109], v[46:49]
	v_mfma_f32_16x16x32_bf16 v[50:53], v[218:221], v[110:113], v[50:53]
	v_mfma_f32_16x16x32_bf16 v[54:57], v[222:225], v[110:113], v[54:57]
	v_mfma_f32_16x16x32_bf16 v[58:61], v[226:229], v[110:113], v[58:61]
	v_mfma_f32_16x16x32_bf16 v[62:65], v[230:233], v[110:113], v[62:65]
	s_waitcnt vmcnt(16)
	ds_read_b128 v[218:221], v214 offset:16384
	ds_read_b128 v[222:225], v214 offset:17408
	ds_read_b128 v[226:229], v214 offset:18432
	ds_read_b128 v[230:233], v214 offset:19456
	s_waitcnt lgkmcnt(4)
	v_mfma_f32_16x16x32_bf16 v[2:5], v[234:237], v[114:117], v[2:5]
	v_mfma_f32_16x16x32_bf16 v[6:9], v[238:241], v[114:117], v[6:9]
	v_mfma_f32_16x16x32_bf16 v[10:13], v[242:245], v[114:117], v[10:13]
	v_mfma_f32_16x16x32_bf16 v[14:17], v[246:249], v[114:117], v[14:17]
	v_mfma_f32_16x16x32_bf16 v[18:21], v[234:237], v[118:121], v[18:21]
	v_mfma_f32_16x16x32_bf16 v[22:25], v[238:241], v[118:121], v[22:25]
	v_mfma_f32_16x16x32_bf16 v[26:29], v[242:245], v[118:121], v[26:29]
	v_mfma_f32_16x16x32_bf16 v[30:33], v[246:249], v[118:121], v[30:33]
	v_mfma_f32_16x16x32_bf16 v[34:37], v[234:237], v[122:125], v[34:37]
	v_mfma_f32_16x16x32_bf16 v[38:41], v[238:241], v[122:125], v[38:41]
	v_mfma_f32_16x16x32_bf16 v[42:45], v[242:245], v[122:125], v[42:45]
	v_mfma_f32_16x16x32_bf16 v[46:49], v[246:249], v[122:125], v[46:49]
	v_mfma_f32_16x16x32_bf16 v[50:53], v[234:237], v[126:129], v[50:53]
	v_mfma_f32_16x16x32_bf16 v[54:57], v[238:241], v[126:129], v[54:57]
	v_mfma_f32_16x16x32_bf16 v[58:61], v[242:245], v[126:129], v[58:61]
	v_mfma_f32_16x16x32_bf16 v[62:65], v[246:249], v[126:129], v[62:65]
	s_waitcnt vmcnt(12)
	ds_read_b128 v[234:237], v214 offset:20480
	ds_read_b128 v[238:241], v214 offset:21504
	ds_read_b128 v[242:245], v214 offset:22528
	ds_read_b128 v[246:249], v214 offset:23552
	s_waitcnt lgkmcnt(4)
	v_mfma_f32_16x16x32_bf16 v[2:5], v[218:221], v[130:133], v[2:5]
	v_mfma_f32_16x16x32_bf16 v[6:9], v[222:225], v[130:133], v[6:9]
	v_mfma_f32_16x16x32_bf16 v[10:13], v[226:229], v[130:133], v[10:13]
	v_mfma_f32_16x16x32_bf16 v[14:17], v[230:233], v[130:133], v[14:17]
	v_mfma_f32_16x16x32_bf16 v[18:21], v[218:221], v[134:137], v[18:21]
	v_mfma_f32_16x16x32_bf16 v[22:25], v[222:225], v[134:137], v[22:25]
	v_mfma_f32_16x16x32_bf16 v[26:29], v[226:229], v[134:137], v[26:29]
	v_mfma_f32_16x16x32_bf16 v[30:33], v[230:233], v[134:137], v[30:33]
	v_mfma_f32_16x16x32_bf16 v[34:37], v[218:221], v[138:141], v[34:37]
	v_mfma_f32_16x16x32_bf16 v[38:41], v[222:225], v[138:141], v[38:41]
	v_mfma_f32_16x16x32_bf16 v[42:45], v[226:229], v[138:141], v[42:45]
	v_mfma_f32_16x16x32_bf16 v[46:49], v[230:233], v[138:141], v[46:49]
	v_mfma_f32_16x16x32_bf16 v[50:53], v[218:221], v[142:145], v[50:53]
	v_mfma_f32_16x16x32_bf16 v[54:57], v[222:225], v[142:145], v[54:57]
	v_mfma_f32_16x16x32_bf16 v[58:61], v[226:229], v[142:145], v[58:61]
	v_mfma_f32_16x16x32_bf16 v[62:65], v[230:233], v[142:145], v[62:65]
	s_waitcnt vmcnt(8)
	ds_read_b128 v[218:221], v214 offset:24576
	ds_read_b128 v[222:225], v214 offset:25600
	ds_read_b128 v[226:229], v214 offset:26624
	ds_read_b128 v[230:233], v214 offset:27648
	s_waitcnt lgkmcnt(4)
	v_mfma_f32_16x16x32_bf16 v[2:5], v[234:237], v[146:149], v[2:5]
	v_mfma_f32_16x16x32_bf16 v[6:9], v[238:241], v[146:149], v[6:9]
	v_mfma_f32_16x16x32_bf16 v[10:13], v[242:245], v[146:149], v[10:13]
	v_mfma_f32_16x16x32_bf16 v[14:17], v[246:249], v[146:149], v[14:17]
	v_mfma_f32_16x16x32_bf16 v[18:21], v[234:237], v[150:153], v[18:21]
	v_mfma_f32_16x16x32_bf16 v[22:25], v[238:241], v[150:153], v[22:25]
	v_mfma_f32_16x16x32_bf16 v[26:29], v[242:245], v[150:153], v[26:29]
	v_mfma_f32_16x16x32_bf16 v[30:33], v[246:249], v[150:153], v[30:33]
	v_mfma_f32_16x16x32_bf16 v[34:37], v[234:237], v[154:157], v[34:37]
	v_mfma_f32_16x16x32_bf16 v[38:41], v[238:241], v[154:157], v[38:41]
	v_mfma_f32_16x16x32_bf16 v[42:45], v[242:245], v[154:157], v[42:45]
	v_mfma_f32_16x16x32_bf16 v[46:49], v[246:249], v[154:157], v[46:49]
	v_mfma_f32_16x16x32_bf16 v[50:53], v[234:237], v[158:161], v[50:53]
	v_mfma_f32_16x16x32_bf16 v[54:57], v[238:241], v[158:161], v[54:57]
	v_mfma_f32_16x16x32_bf16 v[58:61], v[242:245], v[158:161], v[58:61]
	v_mfma_f32_16x16x32_bf16 v[62:65], v[246:249], v[158:161], v[62:65]
	s_waitcnt vmcnt(4)
	ds_read_b128 v[234:237], v214 offset:28672
	ds_read_b128 v[238:241], v214 offset:29696
	ds_read_b128 v[242:245], v214 offset:30720
	ds_read_b128 v[246:249], v214 offset:31744
	s_waitcnt lgkmcnt(4)
	v_mfma_f32_16x16x32_bf16 v[2:5], v[218:221], v[162:165], v[2:5]
	v_mfma_f32_16x16x32_bf16 v[6:9], v[222:225], v[162:165], v[6:9]
	v_mfma_f32_16x16x32_bf16 v[10:13], v[226:229], v[162:165], v[10:13]
	v_mfma_f32_16x16x32_bf16 v[14:17], v[230:233], v[162:165], v[14:17]
	v_mfma_f32_16x16x32_bf16 v[18:21], v[218:221], v[166:169], v[18:21]
	v_mfma_f32_16x16x32_bf16 v[22:25], v[222:225], v[166:169], v[22:25]
	v_mfma_f32_16x16x32_bf16 v[26:29], v[226:229], v[166:169], v[26:29]
	v_mfma_f32_16x16x32_bf16 v[30:33], v[230:233], v[166:169], v[30:33]
	v_mfma_f32_16x16x32_bf16 v[34:37], v[218:221], v[170:173], v[34:37]
	v_mfma_f32_16x16x32_bf16 v[38:41], v[222:225], v[170:173], v[38:41]
	v_mfma_f32_16x16x32_bf16 v[42:45], v[226:229], v[170:173], v[42:45]
	v_mfma_f32_16x16x32_bf16 v[46:49], v[230:233], v[170:173], v[46:49]
	v_mfma_f32_16x16x32_bf16 v[50:53], v[218:221], v[174:177], v[50:53]
	v_mfma_f32_16x16x32_bf16 v[54:57], v[222:225], v[174:177], v[54:57]
	v_mfma_f32_16x16x32_bf16 v[58:61], v[226:229], v[174:177], v[58:61]
	v_mfma_f32_16x16x32_bf16 v[62:65], v[230:233], v[174:177], v[62:65]
	s_waitcnt vmcnt(0)
	s_waitcnt lgkmcnt(0)
	v_mfma_f32_16x16x32_bf16 v[2:5], v[234:237], v[178:181], v[2:5]
	v_mfma_f32_16x16x32_bf16 v[6:9], v[238:241], v[178:181], v[6:9]
	v_mfma_f32_16x16x32_bf16 v[10:13], v[242:245], v[178:181], v[10:13]
	v_mfma_f32_16x16x32_bf16 v[14:17], v[246:249], v[178:181], v[14:17]
	v_mfma_f32_16x16x32_bf16 v[18:21], v[234:237], v[182:185], v[18:21]
	v_mfma_f32_16x16x32_bf16 v[22:25], v[238:241], v[182:185], v[22:25]
	v_mfma_f32_16x16x32_bf16 v[26:29], v[242:245], v[182:185], v[26:29]
	v_mfma_f32_16x16x32_bf16 v[30:33], v[246:249], v[182:185], v[30:33]
	v_mfma_f32_16x16x32_bf16 v[34:37], v[234:237], v[186:189], v[34:37]
	v_mfma_f32_16x16x32_bf16 v[38:41], v[238:241], v[186:189], v[38:41]
	v_mfma_f32_16x16x32_bf16 v[42:45], v[242:245], v[186:189], v[42:45]
	v_mfma_f32_16x16x32_bf16 v[46:49], v[246:249], v[186:189], v[46:49]
	v_mfma_f32_16x16x32_bf16 v[50:53], v[234:237], v[190:193], v[50:53]
	v_mfma_f32_16x16x32_bf16 v[54:57], v[238:241], v[190:193], v[54:57]
	v_mfma_f32_16x16x32_bf16 v[58:61], v[242:245], v[190:193], v[58:61]
	v_mfma_f32_16x16x32_bf16 v[62:65], v[246:249], v[190:193], v[62:65]
	s_nop 7
	s_barrier
	ds_write_b128 v206, v[2:5] offset:0
	ds_write_b128 v206, v[6:9] offset:1024
	ds_write_b128 v206, v[10:13] offset:2048
	ds_write_b128 v206, v[14:17] offset:3072
	ds_write_b128 v206, v[18:21] offset:4096
	ds_write_b128 v206, v[22:25] offset:5120
	ds_write_b128 v206, v[26:29] offset:6144
	ds_write_b128 v206, v[30:33] offset:7168
	ds_write_b128 v206, v[34:37] offset:8192
	ds_write_b128 v206, v[38:41] offset:9216
	ds_write_b128 v206, v[42:45] offset:10240
	ds_write_b128 v206, v[46:49] offset:11264
	ds_write_b128 v206, v[50:53] offset:12288
	ds_write_b128 v206, v[54:57] offset:13312
	ds_write_b128 v206, v[58:61] offset:14336
	ds_write_b128 v206, v[62:65] offset:15360
	s_waitcnt lgkmcnt(0)
	s_barrier
	ds_read_b128 v[2:5], v207 offset:0
	ds_read_b128 v[6:9], v207 offset:16384
	ds_read_b128 v[10:13], v207 offset:32768
	ds_read_b128 v[14:17], v207 offset:49152
	ds_read_b128 v[18:21], v207 offset:1024
	ds_read_b128 v[22:25], v207 offset:17408
	ds_read_b128 v[26:29], v207 offset:33792
	ds_read_b128 v[30:33], v207 offset:50176
	ds_read_b128 v[34:37], v207 offset:2048
	ds_read_b128 v[38:41], v207 offset:18432
	ds_read_b128 v[42:45], v207 offset:34816
	ds_read_b128 v[46:49], v207 offset:51200
	ds_read_b128 v[50:53], v207 offset:3072
	ds_read_b128 v[54:57], v207 offset:19456
	ds_read_b128 v[58:61], v207 offset:35840
	ds_read_b128 v[62:65], v207 offset:52224
	s_waitcnt lgkmcnt(12)
	v_add_f32_e32 v2, v2, v6
	v_add_f32_e32 v3, v3, v7
	v_add_f32_e32 v4, v4, v8
	v_add_f32_e32 v5, v5, v9
	v_add_f32_e32 v10, v10, v14
	v_add_f32_e32 v11, v11, v15
	v_add_f32_e32 v12, v12, v16
	v_add_f32_e32 v13, v13, v17
	v_add_f32_e32 v2, v2, v10
	v_add_f32_e32 v3, v3, v11
	v_add_f32_e32 v4, v4, v12
	v_add_f32_e32 v5, v5, v13
	s_waitcnt lgkmcnt(8)
	v_add_f32_e32 v18, v18, v22
	v_add_f32_e32 v19, v19, v23
	v_add_f32_e32 v20, v20, v24
	v_add_f32_e32 v21, v21, v25
	v_add_f32_e32 v26, v26, v30
	v_add_f32_e32 v27, v27, v31
	v_add_f32_e32 v28, v28, v32
	v_add_f32_e32 v29, v29, v33
	v_add_f32_e32 v18, v18, v26
	v_add_f32_e32 v19, v19, v27
	v_add_f32_e32 v20, v20, v28
	v_add_f32_e32 v21, v21, v29
	s_waitcnt lgkmcnt(4)
	v_add_f32_e32 v34, v34, v38
	v_add_f32_e32 v35, v35, v39
	v_add_f32_e32 v36, v36, v40
	v_add_f32_e32 v37, v37, v41
	v_add_f32_e32 v42, v42, v46
	v_add_f32_e32 v43, v43, v47
	v_add_f32_e32 v44, v44, v48
	v_add_f32_e32 v45, v45, v49
	v_add_f32_e32 v34, v34, v42
	v_add_f32_e32 v35, v35, v43
	v_add_f32_e32 v36, v36, v44
	v_add_f32_e32 v37, v37, v45
	s_waitcnt lgkmcnt(0)
	v_add_f32_e32 v50, v50, v54
	v_add_f32_e32 v51, v51, v55
	v_add_f32_e32 v52, v52, v56
	v_add_f32_e32 v53, v53, v57
	v_add_f32_e32 v58, v58, v62
	v_add_f32_e32 v59, v59, v63
	v_add_f32_e32 v60, v60, v64
	v_add_f32_e32 v61, v61, v65
	v_add_f32_e32 v50, v50, v58
	v_add_f32_e32 v51, v51, v59
	v_add_f32_e32 v52, v52, v60
	v_add_f32_e32 v53, v53, v61
	v_max_f32_e32 v2, 0, v2
	v_max_f32_e32 v3, 0, v3
	v_max_f32_e32 v4, 0, v4
	v_max_f32_e32 v5, 0, v5
	v_mul_f32_e32 v2, v2, v2
	v_mul_f32_e32 v3, v3, v3
	v_mul_f32_e32 v4, v4, v4
	v_mul_f32_e32 v5, v5, v5
	v_cvt_pk_bf16_f32 v210, v2, v3
	v_cvt_pk_bf16_f32 v211, v4, v5
	global_store_dwordx2 v209, v[210:211], s[24:25] offset:0
	v_max_f32_e32 v18, 0, v18
	v_max_f32_e32 v19, 0, v19
	v_max_f32_e32 v20, 0, v20
	v_max_f32_e32 v21, 0, v21
	v_mul_f32_e32 v18, v18, v18
	v_mul_f32_e32 v19, v19, v19
	v_mul_f32_e32 v20, v20, v20
	v_mul_f32_e32 v21, v21, v21
	v_cvt_pk_bf16_f32 v212, v18, v19
	v_cvt_pk_bf16_f32 v213, v20, v21
	global_store_dwordx2 v209, v[212:213], s[24:25] offset:32
	v_max_f32_e32 v34, 0, v34
	v_max_f32_e32 v35, 0, v35
	v_max_f32_e32 v36, 0, v36
	v_max_f32_e32 v37, 0, v37
	v_mul_f32_e32 v34, v34, v34
	v_mul_f32_e32 v35, v35, v35
	v_mul_f32_e32 v36, v36, v36
	v_mul_f32_e32 v37, v37, v37
	v_cvt_pk_bf16_f32 v214, v34, v35
	v_cvt_pk_bf16_f32 v215, v36, v37
	global_store_dwordx2 v209, v[214:215], s[24:25] offset:64
	v_max_f32_e32 v50, 0, v50
	v_max_f32_e32 v51, 0, v51
	v_max_f32_e32 v52, 0, v52
	v_max_f32_e32 v53, 0, v53
	v_mul_f32_e32 v50, v50, v50
	v_mul_f32_e32 v51, v51, v51
	v_mul_f32_e32 v52, v52, v52
	v_mul_f32_e32 v53, v53, v53
	v_cvt_pk_bf16_f32 v216, v50, v51
	v_cvt_pk_bf16_f32 v217, v52, v53
	global_store_dwordx2 v209, v[216:217], s[24:25] offset:96
	s_barrier
	s_add_i32 s12, s12, s3
	s_cmpk_lt_u32 s12, 0x100
	s_cbranch_scc1 .Lsmp5_unit

.Lsg6_wg:
	s_and_b32 s26, s25, 7
	s_lshr_b32 s27, s25, 3
	s_mov_b32 s29, s26
	s_lshr_b32 s28, s27, 1
	s_and_b32 s30, s27, 1
	s_lshl_b32 s30, s30, 3
	s_add_u32 s30, s30, s24
	s_lshl_b32 s31, s29, 10
	s_lshl_b32 s33, s28, 19
	s_add_u32 s33, s33, s31
	s_lshl_b32 s34, s24, 7
	s_add_u32 s33, s33, s34
	s_add_u32 s36, s6, s33
	s_addc_u32 s37, s7, 0
	v_mov_b32_e32 v179, v182
	v_add_u32_e32 v180, 0x40000, v182
	s_lshl_b32 s33, s30, 18
	s_add_u32 s33, s33, s31
	v_add_u32_e32 v178, s33, v182
	s_lshl_b32 s33, s29, 21
	s_lshl_b32 s34, s30, 17
	s_add_u32 s33, s33, s34
	s_lshl_b32 s34, s28, 8
	s_add_u32 s33, s33, s34
	v_add_u32_e32 v181, s33, v183
	s_lshl_b32 s35, s24, 13
	s_cmp_lt_u32 s24, 8
	s_cbranch_scc0 .Lsg6_wonly
	s_add_i32 m0, s35, 0x0
	s_nop 0
	global_load_lds_dwordx4 v179, s[36:37]
	s_add_i32 m0, s35, 0x400
	s_nop 0
	global_load_lds_dwordx4 v180, s[36:37]
	s_add_u32 s36, s36, 32
	s_addc_u32 s37, s37, 0
	s_add_i32 m0, s35, 0x800
	s_nop 0
	global_load_lds_dwordx4 v179, s[36:37]
	s_add_i32 m0, s35, 0xc00
	s_nop 0
	global_load_lds_dwordx4 v180, s[36:37]
	s_add_u32 s36, s36, 32
	s_addc_u32 s37, s37, 0
	s_add_i32 m0, s35, 0x1000
	s_nop 0
	global_load_lds_dwordx4 v179, s[36:37]
	s_add_i32 m0, s35, 0x1400
	s_nop 0
	global_load_lds_dwordx4 v180, s[36:37]
	s_add_u32 s36, s36, 32
	s_addc_u32 s37, s37, 0
	s_add_i32 m0, s35, 0x1800
	s_nop 0
	global_load_lds_dwordx4 v179, s[36:37]
	s_add_i32 m0, s35, 0x1c00
	s_nop 0
	global_load_lds_dwordx4 v180, s[36:37]
	global_load_dwordx4 v[34:37], v178, s[20:21] offset:0
	global_load_dwordx4 v[38:41], v178, s[20:21] offset:32
	global_load_dwordx4 v[42:45], v178, s[20:21] offset:64
	global_load_dwordx4 v[46:49], v178, s[20:21] offset:96
	global_load_dwordx4 v[50:53], v178, s[20:21] offset:128
	global_load_dwordx4 v[54:57], v178, s[20:21] offset:160
	global_load_dwordx4 v[58:61], v178, s[20:21] offset:192
	global_load_dwordx4 v[62:65], v178, s[20:21] offset:224
	global_load_dwordx4 v[66:69], v178, s[20:21] offset:256
	global_load_dwordx4 v[70:73], v178, s[20:21] offset:288
	global_load_dwordx4 v[74:77], v178, s[20:21] offset:320
	global_load_dwordx4 v[78:81], v178, s[20:21] offset:352
	global_load_dwordx4 v[82:85], v178, s[20:21] offset:384
	global_load_dwordx4 v[86:89], v178, s[20:21] offset:416
	global_load_dwordx4 v[90:93], v178, s[20:21] offset:448
	global_load_dwordx4 v[94:97], v178, s[20:21] offset:480
	global_load_dwordx4 v[98:101], v178, s[20:21] offset:512
	global_load_dwordx4 v[102:105], v178, s[20:21] offset:544
	global_load_dwordx4 v[106:109], v178, s[20:21] offset:576
	global_load_dwordx4 v[110:113], v178, s[20:21] offset:608
	global_load_dwordx4 v[114:117], v178, s[20:21] offset:640
	global_load_dwordx4 v[118:121], v178, s[20:21] offset:672
	global_load_dwordx4 v[122:125], v178, s[20:21] offset:704
	global_load_dwordx4 v[126:129], v178, s[20:21] offset:736
	global_load_dwordx4 v[130:133], v178, s[20:21] offset:768
	global_load_dwordx4 v[134:137], v178, s[20:21] offset:800
	global_load_dwordx4 v[138:141], v178, s[20:21] offset:832
	global_load_dwordx4 v[142:145], v178, s[20:21] offset:864
	global_load_dwordx4 v[146:149], v178, s[20:21] offset:896
	global_load_dwordx4 v[150:153], v178, s[20:21] offset:928
	global_load_dwordx4 v[154:157], v178, s[20:21] offset:960
	global_load_dwordx4 v[158:161], v178, s[20:21] offset:992
	s_waitcnt vmcnt(31)
	s_barrier
	s_branch .Lsg6_cmp

.Linp8_unit:
	s_lshr_b32 s29, s12, 3
	s_cmp_gt_u32 s29, 23
	s_cbranch_scc1 .Linp8_next
	s_add_u32 s20, s16, 0x5100000
	s_addc_u32 s21, s17, 0
	s_add_u32 s22, s16, 0x1900000
	s_addc_u32 s23, s17, 0
	s_add_u32 s24, s16, 0xd400000
	s_addc_u32 s25, s17, 0
	s_and_b32 s28, s12, 7
	s_lshl_b32 s29, s29, 1
	s_add_u32 s29, s29, s6
	s_lshr_b32 s30, s29, 3
	s_mul_i32 s28, s28, 6
	s_add_u32 s30, s30, s28
	s_and_b32 s31, s29, 7
	s_lshl_b32 s33, s31, 17
	s_lshl_b32 s34, s30, 17
	v_lshlrev_b32_e32 v215, 11, v202
	v_lshl_add_u32 v215, v203, 4, v215
	v_add_u32_e32 v194, s33, v204
	v_add_u32_e32 v198, s34, v215
	v_add_u32_e32 v195, s33, v204
	v_add_u32_e32 v199, s34, v215
	v_add_u32_e32 v196, s33, v204
	v_add_u32_e32 v200, s34, v215
	v_add_u32_e32 v197, s33, v204
	v_add_u32_e32 v201, s34, v215
	v_add_u32_e32 v195, 0x8000, v195
	v_add_u32_e32 v199, 0x8000, v199
	v_add_u32_e32 v196, 0x10000, v196
	v_add_u32_e32 v200, 0x10000, v200
	v_add_u32_e32 v197, 0x18000, v197
	v_add_u32_e32 v201, 0x18000, v201
	s_mul_i32 s33, s31, 0x60000
	s_lshl_b32 s34, s30, 7
	s_add_u32 s33, s33, s34
	v_add_u32_e32 v211, s33, v209
	s_lshr_b32 s35, s30, 4
	s_and_b32 s36, s30, 15
	s_lshl_b32 s36, s36, 8
	s_mov_b32 s37, 0x3f800000
	s_mov_b32 s42, 1
	s_cmp_eq_u32 s35, 0
	s_cselect_b32 s37, 0x3e38aa3b, s37
	s_cselect_b32 s42, 0, s42
	s_sub_u32 s43, s35, 1
	s_lshl_b32 s43, s43, 24
	s_lshl_b32 s44, s31, 21
	s_add_u32 s43, s43, s44
	s_add_u32 s43, s43, s36
	s_add_u32 s38, s40, s43
	s_addc_u32 s39, s41, 0
	s_add_u32 s38, s38, 0xd844000
	s_addc_u32 s39, s39, 0
	s_lshl_b32 s44, s4, 8
	s_add_u32 s44, s22, s44
	s_addc_u32 s45, s23, 0
	s_lshl_b32 s46, s4, 14
	s_add_i32 m0, s46, 0x0
	s_nop 0
	global_load_lds_dwordx4 v198, s[44:45]
	s_add_i32 m0, s46, 0x400
	s_nop 0
	global_load_lds_dwordx4 v199, s[44:45]
	s_add_i32 m0, s46, 0x800
	s_nop 0
	global_load_lds_dwordx4 v200, s[44:45]
	s_add_i32 m0, s46, 0xc00
	s_nop 0
	global_load_lds_dwordx4 v201, s[44:45]
	s_add_u32 s44, s44, 64
	s_addc_u32 s45, s45, 0
	s_add_i32 m0, s46, 0x1000
	s_nop 0
	global_load_lds_dwordx4 v198, s[44:45]
	s_add_i32 m0, s46, 0x1400
	s_nop 0
	global_load_lds_dwordx4 v199, s[44:45]
	s_add_i32 m0, s46, 0x1800
	s_nop 0
	global_load_lds_dwordx4 v200, s[44:45]
	s_add_i32 m0, s46, 0x1c00
	s_nop 0
	global_load_lds_dwordx4 v201, s[44:45]
	s_add_u32 s44, s44, 64
	s_addc_u32 s45, s45, 0
	s_add_i32 m0, s46, 0x2000
	s_nop 0
	global_load_lds_dwordx4 v198, s[44:45]
	s_add_i32 m0, s46, 0x2400
	s_nop 0
	global_load_lds_dwordx4 v199, s[44:45]
	s_add_i32 m0, s46, 0x2800
	s_nop 0
	global_load_lds_dwordx4 v200, s[44:45]
	s_add_i32 m0, s46, 0x2c00
	s_nop 0
	global_load_lds_dwordx4 v201, s[44:45]
	s_add_u32 s44, s44, 64
	s_addc_u32 s45, s45, 0
	s_add_i32 m0, s46, 0x3000
	s_nop 0
	global_load_lds_dwordx4 v198, s[44:45]
	s_add_i32 m0, s46, 0x3400
	s_nop 0
	global_load_lds_dwordx4 v199, s[44:45]
	s_add_i32 m0, s46, 0x3800
	s_nop 0
	global_load_lds_dwordx4 v200, s[44:45]
	s_add_i32 m0, s46, 0x3c00
	s_nop 0
	global_load_lds_dwordx4 v201, s[44:45]
	global_load_dwordx4 v[66:69], v194, s[20:21] offset:0
	global_load_dwordx4 v[70:73], v195, s[20:21] offset:0
	global_load_dwordx4 v[74:77], v196, s[20:21] offset:0
	global_load_dwordx4 v[78:81], v197, s[20:21] offset:0
	global_load_dwordx4 v[82:85], v194, s[20:21] offset:64
	global_load_dwordx4 v[86:89], v195, s[20:21] offset:64
	global_load_dwordx4 v[90:93], v196, s[20:21] offset:64
	global_load_dwordx4 v[94:97], v197, s[20:21] offset:64
	global_load_dwordx4 v[98:101], v194, s[20:21] offset:128
	global_load_dwordx4 v[102:105], v195, s[20:21] offset:128
	global_load_dwordx4 v[106:109], v196, s[20:21] offset:128
	global_load_dwordx4 v[110:113], v197, s[20:21] offset:128
	global_load_dwordx4 v[114:117], v194, s[20:21] offset:192
	global_load_dwordx4 v[118:121], v195, s[20:21] offset:192
	global_load_dwordx4 v[122:125], v196, s[20:21] offset:192
	global_load_dwordx4 v[126:129], v197, s[20:21] offset:192
	global_load_dwordx4 v[130:133], v194, s[20:21] offset:256
	global_load_dwordx4 v[134:137], v195, s[20:21] offset:256
	global_load_dwordx4 v[138:141], v196, s[20:21] offset:256
	global_load_dwordx4 v[142:145], v197, s[20:21] offset:256
	global_load_dwordx4 v[146:149], v194, s[20:21] offset:320
	global_load_dwordx4 v[150:153], v195, s[20:21] offset:320
	global_load_dwordx4 v[154:157], v196, s[20:21] offset:320
	global_load_dwordx4 v[158:161], v197, s[20:21] offset:320
	global_load_dwordx4 v[162:165], v194, s[20:21] offset:384
	global_load_dwordx4 v[166:169], v195, s[20:21] offset:384
	global_load_dwordx4 v[170:173], v196, s[20:21] offset:384
	global_load_dwordx4 v[174:177], v197, s[20:21] offset:384
	global_load_dwordx4 v[178:181], v194, s[20:21] offset:448
	global_load_dwordx4 v[182:185], v195, s[20:21] offset:448
	global_load_dwordx4 v[186:189], v196, s[20:21] offset:448
	global_load_dwordx4 v[190:193], v197, s[20:21] offset:448
	s_waitcnt vmcnt(28)
	s_barrier
	s_lshl_b32 s47, s5, 15
	v_lshl_add_u32 v214, v205, 4, s47
	ds_read_b128 v[218:221], v214 offset:0
	ds_read_b128 v[222:225], v214 offset:1024
	ds_read_b128 v[226:229], v214 offset:2048
	ds_read_b128 v[230:233], v214 offset:3072
	ds_read_b128 v[234:237], v214 offset:4096
	ds_read_b128 v[238:241], v214 offset:5120
	ds_read_b128 v[242:245], v214 offset:6144
	ds_read_b128 v[246:249], v214 offset:7168
	s_waitcnt lgkmcnt(4)
	v_mfma_f32_16x16x32_bf16 v[2:5], v[218:221], v[66:69], 0
	v_mfma_f32_16x16x32_bf16 v[6:9], v[222:225], v[66:69], 0
	v_mfma_f32_16x16x32_bf16 v[10:13], v[226:229], v[66:69], 0
	v_mfma_f32_16x16x32_bf16 v[14:17], v[230:233], v[66:69], 0
	v_mfma_f32_16x16x32_bf16 v[18:21], v[218:221], v[70:73], 0
	v_mfma_f32_16x16x32_bf16 v[22:25], v[222:225], v[70:73], 0
	v_mfma_f32_16x16x32_bf16 v[26:29], v[226:229], v[70:73], 0
	v_mfma_f32_16x16x32_bf16 v[30:33], v[230:233], v[70:73], 0
	v_mfma_f32_16x16x32_bf16 v[34:37], v[218:221], v[74:77], 0
	v_mfma_f32_16x16x32_bf16 v[38:41], v[222:225], v[74:77], 0
	v_mfma_f32_16x16x32_bf16 v[42:45], v[226:229], v[74:77], 0
	v_mfma_f32_16x16x32_bf16 v[46:49], v[230:233], v[74:77], 0
	v_mfma_f32_16x16x32_bf16 v[50:53], v[218:221], v[78:81], 0
	v_mfma_f32_16x16x32_bf16 v[54:57], v[222:225], v[78:81], 0
	v_mfma_f32_16x16x32_bf16 v[58:61], v[226:229], v[78:81], 0
	v_mfma_f32_16x16x32_bf16 v[62:65], v[230:233], v[78:81], 0
	s_waitcnt vmcnt(24)
	ds_read_b128 v[218:221], v214 offset:8192
	ds_read_b128 v[222:225], v214 offset:9216
	ds_read_b128 v[226:229], v214 offset:10240
	ds_read_b128 v[230:233], v214 offset:11264
	s_waitcnt lgkmcnt(4)
	v_mfma_f32_16x16x32_bf16 v[2:5], v[234:237], v[82:85], v[2:5]
	v_mfma_f32_16x16x32_bf16 v[6:9], v[238:241], v[82:85], v[6:9]
	v_mfma_f32_16x16x32_bf16 v[10:13], v[242:245], v[82:85], v[10:13]
	v_mfma_f32_16x16x32_bf16 v[14:17], v[246:249], v[82:85], v[14:17]
	v_mfma_f32_16x16x32_bf16 v[18:21], v[234:237], v[86:89], v[18:21]
	v_mfma_f32_16x16x32_bf16 v[22:25], v[238:241], v[86:89], v[22:25]
	v_mfma_f32_16x16x32_bf16 v[26:29], v[242:245], v[86:89], v[26:29]
	v_mfma_f32_16x16x32_bf16 v[30:33], v[246:249], v[86:89], v[30:33]
	v_mfma_f32_16x16x32_bf16 v[34:37], v[234:237], v[90:93], v[34:37]
	v_mfma_f32_16x16x32_bf16 v[38:41], v[238:241], v[90:93], v[38:41]
	v_mfma_f32_16x16x32_bf16 v[42:45], v[242:245], v[90:93], v[42:45]
	v_mfma_f32_16x16x32_bf16 v[46:49], v[246:249], v[90:93], v[46:49]
	v_mfma_f32_16x16x32_bf16 v[50:53], v[234:237], v[94:97], v[50:53]
	v_mfma_f32_16x16x32_bf16 v[54:57], v[238:241], v[94:97], v[54:57]
	v_mfma_f32_16x16x32_bf16 v[58:61], v[242:245], v[94:97], v[58:61]
	v_mfma_f32_16x16x32_bf16 v[62:65], v[246:249], v[94:97], v[62:65]
	s_waitcnt vmcnt(20)
	ds_read_b128 v[234:237], v214 offset:12288
	ds_read_b128 v[238:241], v214 offset:13312
	ds_read_b128 v[242:245], v214 offset:14336
	ds_read_b128 v[246:249], v214 offset:15360
	s_waitcnt lgkmcnt(4)
	v_mfma_f32_16x16x32_bf16 v[2:5], v[218:221], v[98:101], v[2:5]
	v_mfma_f32_16x16x32_bf16 v[6:9], v[222:225], v[98:101], v[6:9]
	v_mfma_f32_16x16x32_bf16 v[10:13], v[226:229], v[98:101], v[10:13]
	v_mfma_f32_16x16x32_bf16 v[14:17], v[230:233], v[98:101], v[14:17]
	v_mfma_f32_16x16x32_bf16 v[18:21], v[218:221], v[102:105], v[18:21]
	v_mfma_f32_16x16x32_bf16 v[22:25], v[222:225], v[102:105], v[22:25]
	v_mfma_f32_16x16x32_bf16 v[26:29], v[226:229], v[102:105], v[26:29]
	v_mfma_f32_16x16x32_bf16 v[30:33], v[230:233], v[102:105], v[30:33]
	v_mfma_f32_16x16x32_bf16 v[34:37], v[218:221], v[106:109], v[34:37]
	v_mfma_f32_16x16x32_bf16 v[38:41], v[222:225], v[106:109], v[38:41]
	v_mfma_f32_16x16x32_bf16 v[42:45], v[226:229], v[106:109], v[42:45]
	v_mfma_f32_16x16x32_bf16 v[46:49], v[230:233], v[106:109], v[46:49]
	v_mfma_f32_16x16x32_bf16 v[50:53], v[218:221], v[110:113], v[50:53]
	v_mfma_f32_16x16x32_bf16 v[54:57], v[222:225], v[110:113], v[54:57]
	v_mfma_f32_16x16x32_bf16 v[58:61], v[226:229], v[110:113], v[58:61]
	v_mfma_f32_16x16x32_bf16 v[62:65], v[230:233], v[110:113], v[62:65]
	s_waitcnt vmcnt(16)
	ds_read_b128 v[218:221], v214 offset:16384
	ds_read_b128 v[222:225], v214 offset:17408
	ds_read_b128 v[226:229], v214 offset:18432
	ds_read_b128 v[230:233], v214 offset:19456
	s_waitcnt lgkmcnt(4)
	v_mfma_f32_16x16x32_bf16 v[2:5], v[234:237], v[114:117], v[2:5]
	v_mfma_f32_16x16x32_bf16 v[6:9], v[238:241], v[114:117], v[6:9]
	v_mfma_f32_16x16x32_bf16 v[10:13], v[242:245], v[114:117], v[10:13]
	v_mfma_f32_16x16x32_bf16 v[14:17], v[246:249], v[114:117], v[14:17]
	v_mfma_f32_16x16x32_bf16 v[18:21], v[234:237], v[118:121], v[18:21]
	v_mfma_f32_16x16x32_bf16 v[22:25], v[238:241], v[118:121], v[22:25]
	v_mfma_f32_16x16x32_bf16 v[26:29], v[242:245], v[118:121], v[26:29]
	v_mfma_f32_16x16x32_bf16 v[30:33], v[246:249], v[118:121], v[30:33]
	v_mfma_f32_16x16x32_bf16 v[34:37], v[234:237], v[122:125], v[34:37]
	v_mfma_f32_16x16x32_bf16 v[38:41], v[238:241], v[122:125], v[38:41]
	v_mfma_f32_16x16x32_bf16 v[42:45], v[242:245], v[122:125], v[42:45]
	v_mfma_f32_16x16x32_bf16 v[46:49], v[246:249], v[122:125], v[46:49]
	v_mfma_f32_16x16x32_bf16 v[50:53], v[234:237], v[126:129], v[50:53]
	v_mfma_f32_16x16x32_bf16 v[54:57], v[238:241], v[126:129], v[54:57]
	v_mfma_f32_16x16x32_bf16 v[58:61], v[242:245], v[126:129], v[58:61]
	v_mfma_f32_16x16x32_bf16 v[62:65], v[246:249], v[126:129], v[62:65]
	s_waitcnt vmcnt(12)
	ds_read_b128 v[234:237], v214 offset:20480
	ds_read_b128 v[238:241], v214 offset:21504
	ds_read_b128 v[242:245], v214 offset:22528
	ds_read_b128 v[246:249], v214 offset:23552
	s_waitcnt lgkmcnt(4)
	v_mfma_f32_16x16x32_bf16 v[2:5], v[218:221], v[130:133], v[2:5]
	v_mfma_f32_16x16x32_bf16 v[6:9], v[222:225], v[130:133], v[6:9]
	v_mfma_f32_16x16x32_bf16 v[10:13], v[226:229], v[130:133], v[10:13]
	v_mfma_f32_16x16x32_bf16 v[14:17], v[230:233], v[130:133], v[14:17]
	v_mfma_f32_16x16x32_bf16 v[18:21], v[218:221], v[134:137], v[18:21]
	v_mfma_f32_16x16x32_bf16 v[22:25], v[222:225], v[134:137], v[22:25]
	v_mfma_f32_16x16x32_bf16 v[26:29], v[226:229], v[134:137], v[26:29]
	v_mfma_f32_16x16x32_bf16 v[30:33], v[230:233], v[134:137], v[30:33]
	v_mfma_f32_16x16x32_bf16 v[34:37], v[218:221], v[138:141], v[34:37]
	v_mfma_f32_16x16x32_bf16 v[38:41], v[222:225], v[138:141], v[38:41]
	v_mfma_f32_16x16x32_bf16 v[42:45], v[226:229], v[138:141], v[42:45]
	v_mfma_f32_16x16x32_bf16 v[46:49], v[230:233], v[138:141], v[46:49]
	v_mfma_f32_16x16x32_bf16 v[50:53], v[218:221], v[142:145], v[50:53]
	v_mfma_f32_16x16x32_bf16 v[54:57], v[222:225], v[142:145], v[54:57]
	v_mfma_f32_16x16x32_bf16 v[58:61], v[226:229], v[142:145], v[58:61]
	v_mfma_f32_16x16x32_bf16 v[62:65], v[230:233], v[142:145], v[62:65]
	s_waitcnt vmcnt(8)
	ds_read_b128 v[218:221], v214 offset:24576
	ds_read_b128 v[222:225], v214 offset:25600
	ds_read_b128 v[226:229], v214 offset:26624
	ds_read_b128 v[230:233], v214 offset:27648
	s_waitcnt lgkmcnt(4)
	v_mfma_f32_16x16x32_bf16 v[2:5], v[234:237], v[146:149], v[2:5]
	v_mfma_f32_16x16x32_bf16 v[6:9], v[238:241], v[146:149], v[6:9]
	v_mfma_f32_16x16x32_bf16 v[10:13], v[242:245], v[146:149], v[10:13]
	v_mfma_f32_16x16x32_bf16 v[14:17], v[246:249], v[146:149], v[14:17]
	v_mfma_f32_16x16x32_bf16 v[18:21], v[234:237], v[150:153], v[18:21]
	v_mfma_f32_16x16x32_bf16 v[22:25], v[238:241], v[150:153], v[22:25]
	v_mfma_f32_16x16x32_bf16 v[26:29], v[242:245], v[150:153], v[26:29]
	v_mfma_f32_16x16x32_bf16 v[30:33], v[246:249], v[150:153], v[30:33]
	v_mfma_f32_16x16x32_bf16 v[34:37], v[234:237], v[154:157], v[34:37]
	v_mfma_f32_16x16x32_bf16 v[38:41], v[238:241], v[154:157], v[38:41]
	v_mfma_f32_16x16x32_bf16 v[42:45], v[242:245], v[154:157], v[42:45]
	v_mfma_f32_16x16x32_bf16 v[46:49], v[246:249], v[154:157], v[46:49]
	v_mfma_f32_16x16x32_bf16 v[50:53], v[234:237], v[158:161], v[50:53]
	v_mfma_f32_16x16x32_bf16 v[54:57], v[238:241], v[158:161], v[54:57]
	v_mfma_f32_16x16x32_bf16 v[58:61], v[242:245], v[158:161], v[58:61]
	v_mfma_f32_16x16x32_bf16 v[62:65], v[246:249], v[158:161], v[62:65]
	s_waitcnt vmcnt(4)
	ds_read_b128 v[234:237], v214 offset:28672
	ds_read_b128 v[238:241], v214 offset:29696
	ds_read_b128 v[242:245], v214 offset:30720
	ds_read_b128 v[246:249], v214 offset:31744
	s_waitcnt lgkmcnt(4)
	v_mfma_f32_16x16x32_bf16 v[2:5], v[218:221], v[162:165], v[2:5]
	v_mfma_f32_16x16x32_bf16 v[6:9], v[222:225], v[162:165], v[6:9]
	v_mfma_f32_16x16x32_bf16 v[10:13], v[226:229], v[162:165], v[10:13]
	v_mfma_f32_16x16x32_bf16 v[14:17], v[230:233], v[162:165], v[14:17]
	v_mfma_f32_16x16x32_bf16 v[18:21], v[218:221], v[166:169], v[18:21]
	v_mfma_f32_16x16x32_bf16 v[22:25], v[222:225], v[166:169], v[22:25]
	v_mfma_f32_16x16x32_bf16 v[26:29], v[226:229], v[166:169], v[26:29]
	v_mfma_f32_16x16x32_bf16 v[30:33], v[230:233], v[166:169], v[30:33]
	v_mfma_f32_16x16x32_bf16 v[34:37], v[218:221], v[170:173], v[34:37]
	v_mfma_f32_16x16x32_bf16 v[38:41], v[222:225], v[170:173], v[38:41]
	v_mfma_f32_16x16x32_bf16 v[42:45], v[226:229], v[170:173], v[42:45]
	v_mfma_f32_16x16x32_bf16 v[46:49], v[230:233], v[170:173], v[46:49]
	v_mfma_f32_16x16x32_bf16 v[50:53], v[218:221], v[174:177], v[50:53]
	v_mfma_f32_16x16x32_bf16 v[54:57], v[222:225], v[174:177], v[54:57]
	v_mfma_f32_16x16x32_bf16 v[58:61], v[226:229], v[174:177], v[58:61]
	v_mfma_f32_16x16x32_bf16 v[62:65], v[230:233], v[174:177], v[62:65]
	s_waitcnt vmcnt(0)
	s_waitcnt lgkmcnt(0)
	v_mfma_f32_16x16x32_bf16 v[2:5], v[234:237], v[178:181], v[2:5]
	v_mfma_f32_16x16x32_bf16 v[6:9], v[238:241], v[178:181], v[6:9]
	v_mfma_f32_16x16x32_bf16 v[10:13], v[242:245], v[178:181], v[10:13]
	v_mfma_f32_16x16x32_bf16 v[14:17], v[246:249], v[178:181], v[14:17]
	v_mfma_f32_16x16x32_bf16 v[18:21], v[234:237], v[182:185], v[18:21]
	v_mfma_f32_16x16x32_bf16 v[22:25], v[238:241], v[182:185], v[22:25]
	v_mfma_f32_16x16x32_bf16 v[26:29], v[242:245], v[182:185], v[26:29]
	v_mfma_f32_16x16x32_bf16 v[30:33], v[246:249], v[182:185], v[30:33]
	v_mfma_f32_16x16x32_bf16 v[34:37], v[234:237], v[186:189], v[34:37]
	v_mfma_f32_16x16x32_bf16 v[38:41], v[238:241], v[186:189], v[38:41]
	v_mfma_f32_16x16x32_bf16 v[42:45], v[242:245], v[186:189], v[42:45]
	v_mfma_f32_16x16x32_bf16 v[46:49], v[246:249], v[186:189], v[46:49]
	v_mfma_f32_16x16x32_bf16 v[50:53], v[234:237], v[190:193], v[50:53]
	v_mfma_f32_16x16x32_bf16 v[54:57], v[238:241], v[190:193], v[54:57]
	v_mfma_f32_16x16x32_bf16 v[58:61], v[242:245], v[190:193], v[58:61]
	v_mfma_f32_16x16x32_bf16 v[62:65], v[246:249], v[190:193], v[62:65]
	s_nop 7
	s_barrier
	ds_write_b128 v206, v[2:5] offset:0
	ds_write_b128 v206, v[6:9] offset:1024
	ds_write_b128 v206, v[10:13] offset:2048
	ds_write_b128 v206, v[14:17] offset:3072
	ds_write_b128 v206, v[18:21] offset:4096
	ds_write_b128 v206, v[22:25] offset:5120
	ds_write_b128 v206, v[26:29] offset:6144
	ds_write_b128 v206, v[30:33] offset:7168
	ds_write_b128 v206, v[34:37] offset:8192
	ds_write_b128 v206, v[38:41] offset:9216
	ds_write_b128 v206, v[42:45] offset:10240
	ds_write_b128 v206, v[46:49] offset:11264
	ds_write_b128 v206, v[50:53] offset:12288
	ds_write_b128 v206, v[54:57] offset:13312
	ds_write_b128 v206, v[58:61] offset:14336
	ds_write_b128 v206, v[62:65] offset:15360
	s_waitcnt lgkmcnt(0)
	s_barrier
	ds_read_b128 v[2:5], v207 offset:0
	ds_read_b128 v[6:9], v207 offset:16384
	ds_read_b128 v[10:13], v207 offset:32768
	ds_read_b128 v[14:17], v207 offset:49152
	ds_read_b128 v[18:21], v207 offset:1024
	ds_read_b128 v[22:25], v207 offset:17408
	ds_read_b128 v[26:29], v207 offset:33792
	ds_read_b128 v[30:33], v207 offset:50176
	ds_read_b128 v[34:37], v207 offset:2048
	ds_read_b128 v[38:41], v207 offset:18432
	ds_read_b128 v[42:45], v207 offset:34816
	ds_read_b128 v[46:49], v207 offset:51200
	ds_read_b128 v[50:53], v207 offset:3072
	ds_read_b128 v[54:57], v207 offset:19456
	ds_read_b128 v[58:61], v207 offset:35840
	ds_read_b128 v[62:65], v207 offset:52224
	s_waitcnt lgkmcnt(12)
	v_add_f32_e32 v2, v2, v6
	v_add_f32_e32 v3, v3, v7
	v_add_f32_e32 v4, v4, v8
	v_add_f32_e32 v5, v5, v9
	v_add_f32_e32 v10, v10, v14
	v_add_f32_e32 v11, v11, v15
	v_add_f32_e32 v12, v12, v16
	v_add_f32_e32 v13, v13, v17
	v_add_f32_e32 v2, v2, v10
	v_add_f32_e32 v3, v3, v11
	v_add_f32_e32 v4, v4, v12
	v_add_f32_e32 v5, v5, v13
	s_waitcnt lgkmcnt(8)
	v_add_f32_e32 v18, v18, v22
	v_add_f32_e32 v19, v19, v23
	v_add_f32_e32 v20, v20, v24
	v_add_f32_e32 v21, v21, v25
	v_add_f32_e32 v26, v26, v30
	v_add_f32_e32 v27, v27, v31
	v_add_f32_e32 v28, v28, v32
	v_add_f32_e32 v29, v29, v33
	v_add_f32_e32 v18, v18, v26
	v_add_f32_e32 v19, v19, v27
	v_add_f32_e32 v20, v20, v28
	v_add_f32_e32 v21, v21, v29
	s_waitcnt lgkmcnt(4)
	v_add_f32_e32 v34, v34, v38
	v_add_f32_e32 v35, v35, v39
	v_add_f32_e32 v36, v36, v40
	v_add_f32_e32 v37, v37, v41
	v_add_f32_e32 v42, v42, v46
	v_add_f32_e32 v43, v43, v47
	v_add_f32_e32 v44, v44, v48
	v_add_f32_e32 v45, v45, v49
	v_add_f32_e32 v34, v34, v42
	v_add_f32_e32 v35, v35, v43
	v_add_f32_e32 v36, v36, v44
	v_add_f32_e32 v37, v37, v45
	s_waitcnt lgkmcnt(0)
	v_add_f32_e32 v50, v50, v54
	v_add_f32_e32 v51, v51, v55
	v_add_f32_e32 v52, v52, v56
	v_add_f32_e32 v53, v53, v57
	v_add_f32_e32 v58, v58, v62
	v_add_f32_e32 v59, v59, v63
	v_add_f32_e32 v60, v60, v64
	v_add_f32_e32 v61, v61, v65
	v_add_f32_e32 v50, v50, v58
	v_add_f32_e32 v51, v51, v59
	v_add_f32_e32 v52, v52, v60
	v_add_f32_e32 v53, v53, v61
	s_cmp_eq_u32 s42, 0
	s_cbranch_scc1 .Linp8_nof32
	global_store_dwordx4 v210, v[2:5], s[38:39] offset:0
	global_store_dwordx4 v210, v[18:21], s[38:39] offset:64
	global_store_dwordx4 v210, v[34:37], s[38:39] offset:128
	global_store_dwordx4 v210, v[50:53], s[38:39] offset:192
	s_nop 1

.Lsg10_wg:
	s_and_b32 s26, s25, 7
	s_lshr_b32 s27, s25, 3
	s_lshl_b32 s28, s26, 1
	s_lshr_b32 s29, s27, 4
	s_add_u32 s28, s28, s29
	s_bfe_u32 s29, s27, 0x10003
	s_and_b32 s30, s27, 7
	s_lshl_b32 s31, s24, 3
	s_add_u32 s30, s30, s31
	s_lshl_b32 s31, s29, 10
	s_lshl_b32 s33, s28, 17
	s_add_u32 s33, s33, s31
	s_lshl_b32 s34, s24, 7
	s_add_u32 s33, s33, s34
	s_add_u32 s36, s4, s33
	s_addc_u32 s37, s5, 0
	v_mov_b32_e32 v179, v182
	v_add_u32_e32 v180, 0x10000, v182
	s_lshl_b32 s33, s30, 16
	s_add_u32 s33, s33, s31
	v_add_u32_e32 v178, s33, v182
	s_lshl_b32 s33, s29, 21
	s_lshl_b32 s34, s30, 17
	s_add_u32 s33, s33, s34
	s_lshl_b32 s34, s28, 8
	s_add_u32 s33, s33, s34
	v_add_u32_e32 v181, s33, v183
	s_lshl_b32 s35, s24, 13
	s_cmp_lt_u32 s24, 2
	s_cbranch_scc0 .Lsg10_wonly
	s_add_i32 m0, s35, 0x0
	s_nop 0
	global_load_lds_dwordx4 v179, s[36:37]
	s_add_i32 m0, s35, 0x400
	s_nop 0
	global_load_lds_dwordx4 v180, s[36:37]
	s_add_u32 s36, s36, 32
	s_addc_u32 s37, s37, 0
	s_add_i32 m0, s35, 0x800
	s_nop 0
	global_load_lds_dwordx4 v179, s[36:37]
	s_add_i32 m0, s35, 0xc00
	s_nop 0
	global_load_lds_dwordx4 v180, s[36:37]
	s_add_u32 s36, s36, 32
	s_addc_u32 s37, s37, 0
	s_add_i32 m0, s35, 0x1000
	s_nop 0
	global_load_lds_dwordx4 v179, s[36:37]
	s_add_i32 m0, s35, 0x1400
	s_nop 0
	global_load_lds_dwordx4 v180, s[36:37]
	s_add_u32 s36, s36, 32
	s_addc_u32 s37, s37, 0
	s_add_i32 m0, s35, 0x1800
	s_nop 0
	global_load_lds_dwordx4 v179, s[36:37]
	s_add_i32 m0, s35, 0x1c00
	s_nop 0
	global_load_lds_dwordx4 v180, s[36:37]
	global_load_dwordx4 v[34:37], v178, s[20:21] offset:0
	global_load_dwordx4 v[38:41], v178, s[20:21] offset:32
	global_load_dwordx4 v[42:45], v178, s[20:21] offset:64
	global_load_dwordx4 v[46:49], v178, s[20:21] offset:96
	global_load_dwordx4 v[50:53], v178, s[20:21] offset:128
	global_load_dwordx4 v[54:57], v178, s[20:21] offset:160
	global_load_dwordx4 v[58:61], v178, s[20:21] offset:192
	global_load_dwordx4 v[62:65], v178, s[20:21] offset:224
	global_load_dwordx4 v[66:69], v178, s[20:21] offset:256
	global_load_dwordx4 v[70:73], v178, s[20:21] offset:288
	global_load_dwordx4 v[74:77], v178, s[20:21] offset:320
	global_load_dwordx4 v[78:81], v178, s[20:21] offset:352
	global_load_dwordx4 v[82:85], v178, s[20:21] offset:384
	global_load_dwordx4 v[86:89], v178, s[20:21] offset:416
	global_load_dwordx4 v[90:93], v178, s[20:21] offset:448
	global_load_dwordx4 v[94:97], v178, s[20:21] offset:480
	global_load_dwordx4 v[98:101], v178, s[20:21] offset:512
	global_load_dwordx4 v[102:105], v178, s[20:21] offset:544
	global_load_dwordx4 v[106:109], v178, s[20:21] offset:576
	global_load_dwordx4 v[110:113], v178, s[20:21] offset:608
	global_load_dwordx4 v[114:117], v178, s[20:21] offset:640
	global_load_dwordx4 v[118:121], v178, s[20:21] offset:672
	global_load_dwordx4 v[122:125], v178, s[20:21] offset:704
	global_load_dwordx4 v[126:129], v178, s[20:21] offset:736
	global_load_dwordx4 v[130:133], v178, s[20:21] offset:768
	global_load_dwordx4 v[134:137], v178, s[20:21] offset:800
	global_load_dwordx4 v[138:141], v178, s[20:21] offset:832
	global_load_dwordx4 v[142:145], v178, s[20:21] offset:864
	global_load_dwordx4 v[146:149], v178, s[20:21] offset:896
	global_load_dwordx4 v[150:153], v178, s[20:21] offset:928
	global_load_dwordx4 v[154:157], v178, s[20:21] offset:960
	global_load_dwordx4 v[158:161], v178, s[20:21] offset:992
	s_waitcnt vmcnt(31)
	s_barrier
	s_branch .Lsg10_cmp
	s_branch .Lsg10_issued

.Lsmp12_unit:
	s_add_u32 s20, s16, 0x5100000
	s_addc_u32 s21, s17, 0
	s_add_u32 s22, s16, 0x2100000
	s_addc_u32 s23, s17, 0
	s_add_u32 s24, s16, 0xf400000
	s_addc_u32 s25, s17, 0
	s_and_b32 s28, s12, 7
	s_lshr_b32 s29, s12, 3
	s_lshl_b32 s29, s29, 1
	s_add_u32 s29, s29, s6
	s_lshr_b32 s30, s29, 3
	s_lshl_b32 s28, s28, 3
	s_add_u32 s30, s30, s28
	s_and_b32 s31, s29, 7
	s_lshl_b32 s33, s31, 17
	s_lshl_b32 s34, s30, 17
	v_lshlrev_b32_e32 v215, 11, v202
	v_lshl_add_u32 v215, v203, 4, v215
	v_add_u32_e32 v194, s33, v204
	v_add_u32_e32 v198, s34, v215
	v_add_u32_e32 v195, s33, v204
	v_add_u32_e32 v199, s34, v215
	v_add_u32_e32 v196, s33, v204
	v_add_u32_e32 v200, s34, v215
	v_add_u32_e32 v197, s33, v204
	v_add_u32_e32 v201, s34, v215
	v_add_u32_e32 v195, 0x8000, v195
	v_add_u32_e32 v199, 0x8000, v199
	v_add_u32_e32 v196, 0x10000, v196
	v_add_u32_e32 v200, 0x10000, v200
	v_add_u32_e32 v197, 0x18000, v197
	v_add_u32_e32 v201, 0x18000, v201
	s_lshl_b32 s33, s31, 19
	s_lshl_b32 s34, s30, 7
	s_add_u32 s33, s33, s34
	v_add_u32_e32 v209, s33, v208
	s_lshl_b32 s44, s4, 8
	s_add_u32 s44, s22, s44
	s_addc_u32 s45, s23, 0
	s_lshl_b32 s46, s4, 14
	s_add_i32 m0, s46, 0x0
	s_nop 0
	global_load_lds_dwordx4 v198, s[44:45]
	s_add_i32 m0, s46, 0x400
	s_nop 0
	global_load_lds_dwordx4 v199, s[44:45]
	s_add_i32 m0, s46, 0x800
	s_nop 0
	global_load_lds_dwordx4 v200, s[44:45]
	s_add_i32 m0, s46, 0xc00
	s_nop 0
	global_load_lds_dwordx4 v201, s[44:45]
	s_add_u32 s44, s44, 64
	s_addc_u32 s45, s45, 0
	s_add_i32 m0, s46, 0x1000
	s_nop 0
	global_load_lds_dwordx4 v198, s[44:45]
	s_add_i32 m0, s46, 0x1400
	s_nop 0
	global_load_lds_dwordx4 v199, s[44:45]
	s_add_i32 m0, s46, 0x1800
	s_nop 0
	global_load_lds_dwordx4 v200, s[44:45]
	s_add_i32 m0, s46, 0x1c00
	s_nop 0
	global_load_lds_dwordx4 v201, s[44:45]
	s_add_u32 s44, s44, 64
	s_addc_u32 s45, s45, 0
	s_add_i32 m0, s46, 0x2000
	s_nop 0
	global_load_lds_dwordx4 v198, s[44:45]
	s_add_i32 m0, s46, 0x2400
	s_nop 0
	global_load_lds_dwordx4 v199, s[44:45]
	s_add_i32 m0, s46, 0x2800
	s_nop 0
	global_load_lds_dwordx4 v200, s[44:45]
	s_add_i32 m0, s46, 0x2c00
	s_nop 0
	global_load_lds_dwordx4 v201, s[44:45]
	s_add_u32 s44, s44, 64
	s_addc_u32 s45, s45, 0
	s_add_i32 m0, s46, 0x3000
	s_nop 0
	global_load_lds_dwordx4 v198, s[44:45]
	s_add_i32 m0, s46, 0x3400
	s_nop 0
	global_load_lds_dwordx4 v199, s[44:45]
	s_add_i32 m0, s46, 0x3800
	s_nop 0
	global_load_lds_dwordx4 v200, s[44:45]
	s_add_i32 m0, s46, 0x3c00
	s_nop 0
	global_load_lds_dwordx4 v201, s[44:45]
	global_load_dwordx4 v[66:69], v194, s[20:21] offset:0
	global_load_dwordx4 v[70:73], v195, s[20:21] offset:0
	global_load_dwordx4 v[74:77], v196, s[20:21] offset:0
	global_load_dwordx4 v[78:81], v197, s[20:21] offset:0
	global_load_dwordx4 v[82:85], v194, s[20:21] offset:64
	global_load_dwordx4 v[86:89], v195, s[20:21] offset:64
	global_load_dwordx4 v[90:93], v196, s[20:21] offset:64
	global_load_dwordx4 v[94:97], v197, s[20:21] offset:64
	global_load_dwordx4 v[98:101], v194, s[20:21] offset:128
	global_load_dwordx4 v[102:105], v195, s[20:21] offset:128
	global_load_dwordx4 v[106:109], v196, s[20:21] offset:128
	global_load_dwordx4 v[110:113], v197, s[20:21] offset:128
	global_load_dwordx4 v[114:117], v194, s[20:21] offset:192
	global_load_dwordx4 v[118:121], v195, s[20:21] offset:192
	global_load_dwordx4 v[122:125], v196, s[20:21] offset:192
	global_load_dwordx4 v[126:129], v197, s[20:21] offset:192
	global_load_dwordx4 v[130:133], v194, s[20:21] offset:256
	global_load_dwordx4 v[134:137], v195, s[20:21] offset:256
	global_load_dwordx4 v[138:141], v196, s[20:21] offset:256
	global_load_dwordx4 v[142:145], v197, s[20:21] offset:256
	global_load_dwordx4 v[146:149], v194, s[20:21] offset:320
	global_load_dwordx4 v[150:153], v195, s[20:21] offset:320
	global_load_dwordx4 v[154:157], v196, s[20:21] offset:320
	global_load_dwordx4 v[158:161], v197, s[20:21] offset:320
	global_load_dwordx4 v[162:165], v194, s[20:21] offset:384
	global_load_dwordx4 v[166:169], v195, s[20:21] offset:384
	global_load_dwordx4 v[170:173], v196, s[20:21] offset:384
	global_load_dwordx4 v[174:177], v197, s[20:21] offset:384
	global_load_dwordx4 v[178:181], v194, s[20:21] offset:448
	global_load_dwordx4 v[182:185], v195, s[20:21] offset:448
	global_load_dwordx4 v[186:189], v196, s[20:21] offset:448
	global_load_dwordx4 v[190:193], v197, s[20:21] offset:448
	s_waitcnt vmcnt(28)
	s_barrier
	s_lshl_b32 s47, s5, 15
	v_lshl_add_u32 v214, v205, 4, s47
	ds_read_b128 v[218:221], v214 offset:0
	ds_read_b128 v[222:225], v214 offset:1024
	ds_read_b128 v[226:229], v214 offset:2048
	ds_read_b128 v[230:233], v214 offset:3072
	ds_read_b128 v[234:237], v214 offset:4096
	ds_read_b128 v[238:241], v214 offset:5120
	ds_read_b128 v[242:245], v214 offset:6144
	ds_read_b128 v[246:249], v214 offset:7168
	s_waitcnt lgkmcnt(4)
	v_mfma_f32_16x16x32_bf16 v[2:5], v[218:221], v[66:69], 0
	v_mfma_f32_16x16x32_bf16 v[6:9], v[222:225], v[66:69], 0
	v_mfma_f32_16x16x32_bf16 v[10:13], v[226:229], v[66:69], 0
	v_mfma_f32_16x16x32_bf16 v[14:17], v[230:233], v[66:69], 0
	v_mfma_f32_16x16x32_bf16 v[18:21], v[218:221], v[70:73], 0
	v_mfma_f32_16x16x32_bf16 v[22:25], v[222:225], v[70:73], 0
	v_mfma_f32_16x16x32_bf16 v[26:29], v[226:229], v[70:73], 0
	v_mfma_f32_16x16x32_bf16 v[30:33], v[230:233], v[70:73], 0
	v_mfma_f32_16x16x32_bf16 v[34:37], v[218:221], v[74:77], 0
	v_mfma_f32_16x16x32_bf16 v[38:41], v[222:225], v[74:77], 0
	v_mfma_f32_16x16x32_bf16 v[42:45], v[226:229], v[74:77], 0
	v_mfma_f32_16x16x32_bf16 v[46:49], v[230:233], v[74:77], 0
	v_mfma_f32_16x16x32_bf16 v[50:53], v[218:221], v[78:81], 0
	v_mfma_f32_16x16x32_bf16 v[54:57], v[222:225], v[78:81], 0
	v_mfma_f32_16x16x32_bf16 v[58:61], v[226:229], v[78:81], 0
	v_mfma_f32_16x16x32_bf16 v[62:65], v[230:233], v[78:81], 0
	s_waitcnt vmcnt(24)
	ds_read_b128 v[218:221], v214 offset:8192
	ds_read_b128 v[222:225], v214 offset:9216
	ds_read_b128 v[226:229], v214 offset:10240
	ds_read_b128 v[230:233], v214 offset:11264
	s_waitcnt lgkmcnt(4)
	v_mfma_f32_16x16x32_bf16 v[2:5], v[234:237], v[82:85], v[2:5]
	v_mfma_f32_16x16x32_bf16 v[6:9], v[238:241], v[82:85], v[6:9]
	v_mfma_f32_16x16x32_bf16 v[10:13], v[242:245], v[82:85], v[10:13]
	v_mfma_f32_16x16x32_bf16 v[14:17], v[246:249], v[82:85], v[14:17]
	v_mfma_f32_16x16x32_bf16 v[18:21], v[234:237], v[86:89], v[18:21]
	v_mfma_f32_16x16x32_bf16 v[22:25], v[238:241], v[86:89], v[22:25]
	v_mfma_f32_16x16x32_bf16 v[26:29], v[242:245], v[86:89], v[26:29]
	v_mfma_f32_16x16x32_bf16 v[30:33], v[246:249], v[86:89], v[30:33]
	v_mfma_f32_16x16x32_bf16 v[34:37], v[234:237], v[90:93], v[34:37]
	v_mfma_f32_16x16x32_bf16 v[38:41], v[238:241], v[90:93], v[38:41]
	v_mfma_f32_16x16x32_bf16 v[42:45], v[242:245], v[90:93], v[42:45]
	v_mfma_f32_16x16x32_bf16 v[46:49], v[246:249], v[90:93], v[46:49]
	v_mfma_f32_16x16x32_bf16 v[50:53], v[234:237], v[94:97], v[50:53]
	v_mfma_f32_16x16x32_bf16 v[54:57], v[238:241], v[94:97], v[54:57]
	v_mfma_f32_16x16x32_bf16 v[58:61], v[242:245], v[94:97], v[58:61]
	v_mfma_f32_16x16x32_bf16 v[62:65], v[246:249], v[94:97], v[62:65]
	s_waitcnt vmcnt(20)
	ds_read_b128 v[234:237], v214 offset:12288
	ds_read_b128 v[238:241], v214 offset:13312
	ds_read_b128 v[242:245], v214 offset:14336
	ds_read_b128 v[246:249], v214 offset:15360
	s_waitcnt lgkmcnt(4)
	v_mfma_f32_16x16x32_bf16 v[2:5], v[218:221], v[98:101], v[2:5]
	v_mfma_f32_16x16x32_bf16 v[6:9], v[222:225], v[98:101], v[6:9]
	v_mfma_f32_16x16x32_bf16 v[10:13], v[226:229], v[98:101], v[10:13]
	v_mfma_f32_16x16x32_bf16 v[14:17], v[230:233], v[98:101], v[14:17]
	v_mfma_f32_16x16x32_bf16 v[18:21], v[218:221], v[102:105], v[18:21]
	v_mfma_f32_16x16x32_bf16 v[22:25], v[222:225], v[102:105], v[22:25]
	v_mfma_f32_16x16x32_bf16 v[26:29], v[226:229], v[102:105], v[26:29]
	v_mfma_f32_16x16x32_bf16 v[30:33], v[230:233], v[102:105], v[30:33]
	v_mfma_f32_16x16x32_bf16 v[34:37], v[218:221], v[106:109], v[34:37]
	v_mfma_f32_16x16x32_bf16 v[38:41], v[222:225], v[106:109], v[38:41]
	v_mfma_f32_16x16x32_bf16 v[42:45], v[226:229], v[106:109], v[42:45]
	v_mfma_f32_16x16x32_bf16 v[46:49], v[230:233], v[106:109], v[46:49]
	v_mfma_f32_16x16x32_bf16 v[50:53], v[218:221], v[110:113], v[50:53]
	v_mfma_f32_16x16x32_bf16 v[54:57], v[222:225], v[110:113], v[54:57]
	v_mfma_f32_16x16x32_bf16 v[58:61], v[226:229], v[110:113], v[58:61]
	v_mfma_f32_16x16x32_bf16 v[62:65], v[230:233], v[110:113], v[62:65]
	s_waitcnt vmcnt(16)
	ds_read_b128 v[218:221], v214 offset:16384
	ds_read_b128 v[222:225], v214 offset:17408
	ds_read_b128 v[226:229], v214 offset:18432
	ds_read_b128 v[230:233], v214 offset:19456
	s_waitcnt lgkmcnt(4)
	v_mfma_f32_16x16x32_bf16 v[2:5], v[234:237], v[114:117], v[2:5]
	v_mfma_f32_16x16x32_bf16 v[6:9], v[238:241], v[114:117], v[6:9]
	v_mfma_f32_16x16x32_bf16 v[10:13], v[242:245], v[114:117], v[10:13]
	v_mfma_f32_16x16x32_bf16 v[14:17], v[246:249], v[114:117], v[14:17]
	v_mfma_f32_16x16x32_bf16 v[18:21], v[234:237], v[118:121], v[18:21]
	v_mfma_f32_16x16x32_bf16 v[22:25], v[238:241], v[118:121], v[22:25]
	v_mfma_f32_16x16x32_bf16 v[26:29], v[242:245], v[118:121], v[26:29]
	v_mfma_f32_16x16x32_bf16 v[30:33], v[246:249], v[118:121], v[30:33]
	v_mfma_f32_16x16x32_bf16 v[34:37], v[234:237], v[122:125], v[34:37]
	v_mfma_f32_16x16x32_bf16 v[38:41], v[238:241], v[122:125], v[38:41]
	v_mfma_f32_16x16x32_bf16 v[42:45], v[242:245], v[122:125], v[42:45]
	v_mfma_f32_16x16x32_bf16 v[46:49], v[246:249], v[122:125], v[46:49]
	v_mfma_f32_16x16x32_bf16 v[50:53], v[234:237], v[126:129], v[50:53]
	v_mfma_f32_16x16x32_bf16 v[54:57], v[238:241], v[126:129], v[54:57]
	v_mfma_f32_16x16x32_bf16 v[58:61], v[242:245], v[126:129], v[58:61]
	v_mfma_f32_16x16x32_bf16 v[62:65], v[246:249], v[126:129], v[62:65]
	s_waitcnt vmcnt(12)
	ds_read_b128 v[234:237], v214 offset:20480
	ds_read_b128 v[238:241], v214 offset:21504
	ds_read_b128 v[242:245], v214 offset:22528
	ds_read_b128 v[246:249], v214 offset:23552
	s_waitcnt lgkmcnt(4)
	v_mfma_f32_16x16x32_bf16 v[2:5], v[218:221], v[130:133], v[2:5]
	v_mfma_f32_16x16x32_bf16 v[6:9], v[222:225], v[130:133], v[6:9]
	v_mfma_f32_16x16x32_bf16 v[10:13], v[226:229], v[130:133], v[10:13]
	v_mfma_f32_16x16x32_bf16 v[14:17], v[230:233], v[130:133], v[14:17]
	v_mfma_f32_16x16x32_bf16 v[18:21], v[218:221], v[134:137], v[18:21]
	v_mfma_f32_16x16x32_bf16 v[22:25], v[222:225], v[134:137], v[22:25]
	v_mfma_f32_16x16x32_bf16 v[26:29], v[226:229], v[134:137], v[26:29]
	v_mfma_f32_16x16x32_bf16 v[30:33], v[230:233], v[134:137], v[30:33]
	v_mfma_f32_16x16x32_bf16 v[34:37], v[218:221], v[138:141], v[34:37]
	v_mfma_f32_16x16x32_bf16 v[38:41], v[222:225], v[138:141], v[38:41]
	v_mfma_f32_16x16x32_bf16 v[42:45], v[226:229], v[138:141], v[42:45]
	v_mfma_f32_16x16x32_bf16 v[46:49], v[230:233], v[138:141], v[46:49]
	v_mfma_f32_16x16x32_bf16 v[50:53], v[218:221], v[142:145], v[50:53]
	v_mfma_f32_16x16x32_bf16 v[54:57], v[222:225], v[142:145], v[54:57]
	v_mfma_f32_16x16x32_bf16 v[58:61], v[226:229], v[142:145], v[58:61]
	v_mfma_f32_16x16x32_bf16 v[62:65], v[230:233], v[142:145], v[62:65]
	s_waitcnt vmcnt(8)
	ds_read_b128 v[218:221], v214 offset:24576
	ds_read_b128 v[222:225], v214 offset:25600
	ds_read_b128 v[226:229], v214 offset:26624
	ds_read_b128 v[230:233], v214 offset:27648
	s_waitcnt lgkmcnt(4)
	v_mfma_f32_16x16x32_bf16 v[2:5], v[234:237], v[146:149], v[2:5]
	v_mfma_f32_16x16x32_bf16 v[6:9], v[238:241], v[146:149], v[6:9]
	v_mfma_f32_16x16x32_bf16 v[10:13], v[242:245], v[146:149], v[10:13]
	v_mfma_f32_16x16x32_bf16 v[14:17], v[246:249], v[146:149], v[14:17]
	v_mfma_f32_16x16x32_bf16 v[18:21], v[234:237], v[150:153], v[18:21]
	v_mfma_f32_16x16x32_bf16 v[22:25], v[238:241], v[150:153], v[22:25]
	v_mfma_f32_16x16x32_bf16 v[26:29], v[242:245], v[150:153], v[26:29]
	v_mfma_f32_16x16x32_bf16 v[30:33], v[246:249], v[150:153], v[30:33]
	v_mfma_f32_16x16x32_bf16 v[34:37], v[234:237], v[154:157], v[34:37]
	v_mfma_f32_16x16x32_bf16 v[38:41], v[238:241], v[154:157], v[38:41]
	v_mfma_f32_16x16x32_bf16 v[42:45], v[242:245], v[154:157], v[42:45]
	v_mfma_f32_16x16x32_bf16 v[46:49], v[246:249], v[154:157], v[46:49]
	v_mfma_f32_16x16x32_bf16 v[50:53], v[234:237], v[158:161], v[50:53]
	v_mfma_f32_16x16x32_bf16 v[54:57], v[238:241], v[158:161], v[54:57]
	v_mfma_f32_16x16x32_bf16 v[58:61], v[242:245], v[158:161], v[58:61]
	v_mfma_f32_16x16x32_bf16 v[62:65], v[246:249], v[158:161], v[62:65]
	s_waitcnt vmcnt(4)
	ds_read_b128 v[234:237], v214 offset:28672
	ds_read_b128 v[238:241], v214 offset:29696
	ds_read_b128 v[242:245], v214 offset:30720
	ds_read_b128 v[246:249], v214 offset:31744
	s_waitcnt lgkmcnt(4)
	v_mfma_f32_16x16x32_bf16 v[2:5], v[218:221], v[162:165], v[2:5]
	v_mfma_f32_16x16x32_bf16 v[6:9], v[222:225], v[162:165], v[6:9]
	v_mfma_f32_16x16x32_bf16 v[10:13], v[226:229], v[162:165], v[10:13]
	v_mfma_f32_16x16x32_bf16 v[14:17], v[230:233], v[162:165], v[14:17]
	v_mfma_f32_16x16x32_bf16 v[18:21], v[218:221], v[166:169], v[18:21]
	v_mfma_f32_16x16x32_bf16 v[22:25], v[222:225], v[166:169], v[22:25]
	v_mfma_f32_16x16x32_bf16 v[26:29], v[226:229], v[166:169], v[26:29]
	v_mfma_f32_16x16x32_bf16 v[30:33], v[230:233], v[166:169], v[30:33]
	v_mfma_f32_16x16x32_bf16 v[34:37], v[218:221], v[170:173], v[34:37]
	v_mfma_f32_16x16x32_bf16 v[38:41], v[222:225], v[170:173], v[38:41]
	v_mfma_f32_16x16x32_bf16 v[42:45], v[226:229], v[170:173], v[42:45]
	v_mfma_f32_16x16x32_bf16 v[46:49], v[230:233], v[170:173], v[46:49]
	v_mfma_f32_16x16x32_bf16 v[50:53], v[218:221], v[174:177], v[50:53]
	v_mfma_f32_16x16x32_bf16 v[54:57], v[222:225], v[174:177], v[54:57]
	v_mfma_f32_16x16x32_bf16 v[58:61], v[226:229], v[174:177], v[58:61]
	v_mfma_f32_16x16x32_bf16 v[62:65], v[230:233], v[174:177], v[62:65]
	s_waitcnt vmcnt(0)
	s_waitcnt lgkmcnt(0)
	v_mfma_f32_16x16x32_bf16 v[2:5], v[234:237], v[178:181], v[2:5]
	v_mfma_f32_16x16x32_bf16 v[6:9], v[238:241], v[178:181], v[6:9]
	v_mfma_f32_16x16x32_bf16 v[10:13], v[242:245], v[178:181], v[10:13]
	v_mfma_f32_16x16x32_bf16 v[14:17], v[246:249], v[178:181], v[14:17]
	v_mfma_f32_16x16x32_bf16 v[18:21], v[234:237], v[182:185], v[18:21]
	v_mfma_f32_16x16x32_bf16 v[22:25], v[238:241], v[182:185], v[22:25]
	v_mfma_f32_16x16x32_bf16 v[26:29], v[242:245], v[182:185], v[26:29]
	v_mfma_f32_16x16x32_bf16 v[30:33], v[246:249], v[182:185], v[30:33]
	v_mfma_f32_16x16x32_bf16 v[34:37], v[234:237], v[186:189], v[34:37]
	v_mfma_f32_16x16x32_bf16 v[38:41], v[238:241], v[186:189], v[38:41]
	v_mfma_f32_16x16x32_bf16 v[42:45], v[242:245], v[186:189], v[42:45]
	v_mfma_f32_16x16x32_bf16 v[46:49], v[246:249], v[186:189], v[46:49]
	v_mfma_f32_16x16x32_bf16 v[50:53], v[234:237], v[190:193], v[50:53]
	v_mfma_f32_16x16x32_bf16 v[54:57], v[238:241], v[190:193], v[54:57]
	v_mfma_f32_16x16x32_bf16 v[58:61], v[242:245], v[190:193], v[58:61]
	v_mfma_f32_16x16x32_bf16 v[62:65], v[246:249], v[190:193], v[62:65]
	s_nop 7
	s_barrier
	ds_write_b128 v206, v[2:5] offset:0
	ds_write_b128 v206, v[6:9] offset:1024
	ds_write_b128 v206, v[10:13] offset:2048
	ds_write_b128 v206, v[14:17] offset:3072
	ds_write_b128 v206, v[18:21] offset:4096
	ds_write_b128 v206, v[22:25] offset:5120
	ds_write_b128 v206, v[26:29] offset:6144
	ds_write_b128 v206, v[30:33] offset:7168
	ds_write_b128 v206, v[34:37] offset:8192
	ds_write_b128 v206, v[38:41] offset:9216
	ds_write_b128 v206, v[42:45] offset:10240
	ds_write_b128 v206, v[46:49] offset:11264
	ds_write_b128 v206, v[50:53] offset:12288
	ds_write_b128 v206, v[54:57] offset:13312
	ds_write_b128 v206, v[58:61] offset:14336
	ds_write_b128 v206, v[62:65] offset:15360
	s_waitcnt lgkmcnt(0)
	s_barrier
	ds_read_b128 v[2:5], v207 offset:0
	ds_read_b128 v[6:9], v207 offset:16384
	ds_read_b128 v[10:13], v207 offset:32768
	ds_read_b128 v[14:17], v207 offset:49152
	ds_read_b128 v[18:21], v207 offset:1024
	ds_read_b128 v[22:25], v207 offset:17408
	ds_read_b128 v[26:29], v207 offset:33792
	ds_read_b128 v[30:33], v207 offset:50176
	ds_read_b128 v[34:37], v207 offset:2048
	ds_read_b128 v[38:41], v207 offset:18432
	ds_read_b128 v[42:45], v207 offset:34816
	ds_read_b128 v[46:49], v207 offset:51200
	ds_read_b128 v[50:53], v207 offset:3072
	ds_read_b128 v[54:57], v207 offset:19456
	ds_read_b128 v[58:61], v207 offset:35840
	ds_read_b128 v[62:65], v207 offset:52224
	s_waitcnt lgkmcnt(12)
	v_add_f32_e32 v2, v2, v6
	v_add_f32_e32 v3, v3, v7
	v_add_f32_e32 v4, v4, v8
	v_add_f32_e32 v5, v5, v9
	v_add_f32_e32 v10, v10, v14
	v_add_f32_e32 v11, v11, v15
	v_add_f32_e32 v12, v12, v16
	v_add_f32_e32 v13, v13, v17
	v_add_f32_e32 v2, v2, v10
	v_add_f32_e32 v3, v3, v11
	v_add_f32_e32 v4, v4, v12
	v_add_f32_e32 v5, v5, v13
	s_waitcnt lgkmcnt(8)
	v_add_f32_e32 v18, v18, v22
	v_add_f32_e32 v19, v19, v23
	v_add_f32_e32 v20, v20, v24
	v_add_f32_e32 v21, v21, v25
	v_add_f32_e32 v26, v26, v30
	v_add_f32_e32 v27, v27, v31
	v_add_f32_e32 v28, v28, v32
	v_add_f32_e32 v29, v29, v33
	v_add_f32_e32 v18, v18, v26
	v_add_f32_e32 v19, v19, v27
	v_add_f32_e32 v20, v20, v28
	v_add_f32_e32 v21, v21, v29
	s_waitcnt lgkmcnt(4)
	v_add_f32_e32 v34, v34, v38
	v_add_f32_e32 v35, v35, v39
	v_add_f32_e32 v36, v36, v40
	v_add_f32_e32 v37, v37, v41
	v_add_f32_e32 v42, v42, v46
	v_add_f32_e32 v43, v43, v47
	v_add_f32_e32 v44, v44, v48
	v_add_f32_e32 v45, v45, v49
	v_add_f32_e32 v34, v34, v42
	v_add_f32_e32 v35, v35, v43
	v_add_f32_e32 v36, v36, v44
	v_add_f32_e32 v37, v37, v45
	s_waitcnt lgkmcnt(0)
	v_add_f32_e32 v50, v50, v54
	v_add_f32_e32 v51, v51, v55
	v_add_f32_e32 v52, v52, v56
	v_add_f32_e32 v53, v53, v57
	v_add_f32_e32 v58, v58, v62
	v_add_f32_e32 v59, v59, v63
	v_add_f32_e32 v60, v60, v64
	v_add_f32_e32 v61, v61, v65
	v_add_f32_e32 v50, v50, v58
	v_add_f32_e32 v51, v51, v59
	v_add_f32_e32 v52, v52, v60
	v_add_f32_e32 v53, v53, v61
	v_max_f32_e32 v2, 0, v2
	v_max_f32_e32 v3, 0, v3
	v_max_f32_e32 v4, 0, v4
	v_max_f32_e32 v5, 0, v5
	v_mul_f32_e32 v2, v2, v2
	v_mul_f32_e32 v3, v3, v3
	v_mul_f32_e32 v4, v4, v4
	v_mul_f32_e32 v5, v5, v5
	v_cvt_pk_bf16_f32 v210, v2, v3
	v_cvt_pk_bf16_f32 v211, v4, v5
	global_store_dwordx2 v209, v[210:211], s[24:25] offset:0
	v_max_f32_e32 v18, 0, v18
	v_max_f32_e32 v19, 0, v19
	v_max_f32_e32 v20, 0, v20
	v_max_f32_e32 v21, 0, v21
	v_mul_f32_e32 v18, v18, v18
	v_mul_f32_e32 v19, v19, v19
	v_mul_f32_e32 v20, v20, v20
	v_mul_f32_e32 v21, v21, v21
	v_cvt_pk_bf16_f32 v212, v18, v19
	v_cvt_pk_bf16_f32 v213, v20, v21
	global_store_dwordx2 v209, v[212:213], s[24:25] offset:32
	v_max_f32_e32 v34, 0, v34
	v_max_f32_e32 v35, 0, v35
	v_max_f32_e32 v36, 0, v36
	v_max_f32_e32 v37, 0, v37
	v_mul_f32_e32 v34, v34, v34
	v_mul_f32_e32 v35, v35, v35
	v_mul_f32_e32 v36, v36, v36
	v_mul_f32_e32 v37, v37, v37
	v_cvt_pk_bf16_f32 v214, v34, v35
	v_cvt_pk_bf16_f32 v215, v36, v37
	global_store_dwordx2 v209, v[214:215], s[24:25] offset:64
	v_max_f32_e32 v50, 0, v50
	v_max_f32_e32 v51, 0, v51
	v_max_f32_e32 v52, 0, v52
	v_max_f32_e32 v53, 0, v53
	v_mul_f32_e32 v50, v50, v50
	v_mul_f32_e32 v51, v51, v51
	v_mul_f32_e32 v52, v52, v52
	v_mul_f32_e32 v53, v53, v53
	v_cvt_pk_bf16_f32 v216, v50, v51
	v_cvt_pk_bf16_f32 v217, v52, v53
	global_store_dwordx2 v209, v[216:217], s[24:25] offset:96
	s_barrier
	s_add_i32 s12, s12, s3
	s_cmpk_lt_u32 s12, 0x100
	s_cbranch_scc1 .Lsmp12_unit

.Lsg13_wg:
	s_and_b32 s26, s25, 7
	s_lshr_b32 s27, s25, 3
	s_mov_b32 s29, s26
	s_lshr_b32 s28, s27, 1
	s_and_b32 s30, s27, 1
	s_lshl_b32 s30, s30, 3
	s_add_u32 s30, s30, s24
	s_lshl_b32 s31, s29, 10
	s_lshl_b32 s33, s28, 19
	s_add_u32 s33, s33, s31
	s_lshl_b32 s34, s24, 7
	s_add_u32 s33, s33, s34
	s_add_u32 s36, s4, s33
	s_addc_u32 s37, s5, 0
	v_mov_b32_e32 v179, v182
	v_add_u32_e32 v180, 0x40000, v182
	s_lshl_b32 s33, s30, 18
	s_add_u32 s33, s33, s31
	v_add_u32_e32 v178, s33, v182
	s_lshl_b32 s33, s29, 21
	s_lshl_b32 s34, s30, 17
	s_add_u32 s33, s33, s34
	s_lshl_b32 s34, s28, 8
	s_add_u32 s33, s33, s34
	v_add_u32_e32 v181, s33, v183
	s_lshl_b32 s35, s24, 13
	s_cmp_lt_u32 s24, 8
	s_cbranch_scc0 .Lsg13_wonly
	s_add_i32 m0, s35, 0x0
	s_nop 0
	global_load_lds_dwordx4 v179, s[36:37]
	s_add_i32 m0, s35, 0x400
	s_nop 0
	global_load_lds_dwordx4 v180, s[36:37]
	s_add_u32 s36, s36, 32
	s_addc_u32 s37, s37, 0
	s_add_i32 m0, s35, 0x800
	s_nop 0
	global_load_lds_dwordx4 v179, s[36:37]
	s_add_i32 m0, s35, 0xc00
	s_nop 0
	global_load_lds_dwordx4 v180, s[36:37]
	s_add_u32 s36, s36, 32
	s_addc_u32 s37, s37, 0
	s_add_i32 m0, s35, 0x1000
	s_nop 0
	global_load_lds_dwordx4 v179, s[36:37]
	s_add_i32 m0, s35, 0x1400
	s_nop 0
	global_load_lds_dwordx4 v180, s[36:37]
	s_add_u32 s36, s36, 32
	s_addc_u32 s37, s37, 0
	s_add_i32 m0, s35, 0x1800
	s_nop 0
	global_load_lds_dwordx4 v179, s[36:37]
	s_add_i32 m0, s35, 0x1c00
	s_nop 0
	global_load_lds_dwordx4 v180, s[36:37]
	global_load_dwordx4 v[34:37], v178, s[20:21] offset:0
	global_load_dwordx4 v[38:41], v178, s[20:21] offset:32
	global_load_dwordx4 v[42:45], v178, s[20:21] offset:64
	global_load_dwordx4 v[46:49], v178, s[20:21] offset:96
	global_load_dwordx4 v[50:53], v178, s[20:21] offset:128
	global_load_dwordx4 v[54:57], v178, s[20:21] offset:160
	global_load_dwordx4 v[58:61], v178, s[20:21] offset:192
	global_load_dwordx4 v[62:65], v178, s[20:21] offset:224
	global_load_dwordx4 v[66:69], v178, s[20:21] offset:256
	global_load_dwordx4 v[70:73], v178, s[20:21] offset:288
	global_load_dwordx4 v[74:77], v178, s[20:21] offset:320
	global_load_dwordx4 v[78:81], v178, s[20:21] offset:352
	global_load_dwordx4 v[82:85], v178, s[20:21] offset:384
	global_load_dwordx4 v[86:89], v178, s[20:21] offset:416
	global_load_dwordx4 v[90:93], v178, s[20:21] offset:448
	global_load_dwordx4 v[94:97], v178, s[20:21] offset:480
	global_load_dwordx4 v[98:101], v178, s[20:21] offset:512
	global_load_dwordx4 v[102:105], v178, s[20:21] offset:544
	global_load_dwordx4 v[106:109], v178, s[20:21] offset:576
	global_load_dwordx4 v[110:113], v178, s[20:21] offset:608
	global_load_dwordx4 v[114:117], v178, s[20:21] offset:640
	global_load_dwordx4 v[118:121], v178, s[20:21] offset:672
	global_load_dwordx4 v[122:125], v178, s[20:21] offset:704
	global_load_dwordx4 v[126:129], v178, s[20:21] offset:736
	global_load_dwordx4 v[130:133], v178, s[20:21] offset:768
	global_load_dwordx4 v[134:137], v178, s[20:21] offset:800
	global_load_dwordx4 v[138:141], v178, s[20:21] offset:832
	global_load_dwordx4 v[142:145], v178, s[20:21] offset:864
	global_load_dwordx4 v[146:149], v178, s[20:21] offset:896
	global_load_dwordx4 v[150:153], v178, s[20:21] offset:928
	global_load_dwordx4 v[154:157], v178, s[20:21] offset:960
	global_load_dwordx4 v[158:161], v178, s[20:21] offset:992
	s_waitcnt vmcnt(31)
	s_barrier
	s_branch .Lsg13_cmp
